# speedup vs baseline: 1.0111x; 1.0111x over previous
; __device__ __forceinline__ float bflo(unsigned w) { return __uint_as_float(w << 16); }
; __device__ __forceinline__ float bfhi(unsigned w) { return __uint_as_float(w & 0xffff0000u); }
; __device__ __forceinline__ f32x4 ld_row4(const float* srcL, const bf16_t* xb_in, const float* srcC, int row, int idx) {
;     ...
;     if (xb_in) { const u32x2 t = ((const u32x2*)(xb_in + (size_t)row * DM))[idx]; return (f32x4){bflo(t.x), bfhi(t.x), bflo(t.y), bfhi(t.y)}; }
; __global__ void __launch_bounds__(NTHR, 2) mk_fwd(Args a) {
;     ...
;                     for (int row = gw; row < ML; row += NGW) {
;                         f32x4* xr = (f32x4*)(xres + (size_t)row * DM); f32x4 v[4]; float s = 0.f;
; #pragma unroll
;                         for (int j = 0; j < 4; ++j) { v[j] = ld_row4(nullptr, XB, nullptr, row, lane + 64 * j); s += (v[j].x * v[j].x + v[j].y * v[j].y) + (v[j].z * v[j].z + v[j].w * v[j].w); }
;                         s = wave_sum(s, lane); const float rstd = 1.0f / sqrtf(s * (1.0f / DM) + 1e-6f);
; #pragma unroll
;                         for (int j = 0; j < 4; ++j) xr[lane + 64 * j] = v[j] * rstd * ((const f32x4*)final_g)[lane + 64 * j];
;                     }
.Lnf_begin:
	s_cmp_lt_i32 s10, 0x8000
	s_cbranch_scc0 .Lnf_done
	v_lshlrev_b32_e32 v86, 3, v249
	v_lshlrev_b32_e32 v74, 4, v249
	v_lshlrev_b32_e32 v3, 2, v249
	v_xor_b32_e32 v1, 4, v3
	v_xor_b32_e32 v71, 8, v3
	v_xor_b32_e32 v73, 16, v3
	v_xor_b32_e32 v96, 32, v3
	v_xor_b32_e32 v97, 64, v3
	v_xor_b32_e32 v98, 0x80, v3
	s_load_dwordx4 s[84:87], s[28:29], 0x88
	s_mov_b32 s8, s10
	s_lshl_b32 s13, s12, 11
	s_lshl_b32 s3, s12, 12
	s_ashr_i32 s11, s10, 31
	s_lshl_b64 s[6:7], s[10:11], 11
	s_add_u32 s34, s30, s6
	s_addc_u32 s35, s31, s7
	s_lshl_b64 s[6:7], s[10:11], 12
	s_waitcnt lgkmcnt(0)
	s_add_u32 s36, s86, s6
	s_addc_u32 s37, s87, s7
	s_mov_b32 s46, s10
	global_load_dwordx4 v[6:9], v74, s[84:85]
	global_load_dwordx4 v[14:17], v74, s[84:85] offset:1024
	global_load_dwordx4 v[26:29], v74, s[84:85] offset:2048
	global_load_dwordx4 v[38:41], v74, s[84:85] offset:3072
	global_load_dwordx2 v[100:101], v86, s[34:35]
	global_load_dwordx2 v[102:103], v86, s[34:35] offset:512
	global_load_dwordx2 v[104:105], v86, s[34:35] offset:1024
	global_load_dwordx2 v[106:107], v86, s[34:35] offset:1536
	s_add_i32 s11, s46, s12
	s_cmp_lt_i32 s11, 0x8000
	s_cselect_b32 s46, s11, s46
	s_cselect_b32 s11, s13, 0
	s_add_u32 s34, s34, s11
	s_addc_u32 s35, s35, 0
	global_load_dwordx2 v[108:109], v86, s[34:35]
	global_load_dwordx2 v[110:111], v86, s[34:35] offset:512
	global_load_dwordx2 v[112:113], v86, s[34:35] offset:1024
	global_load_dwordx2 v[114:115], v86, s[34:35] offset:1536
	s_add_i32 s11, s46, s12
	s_cmp_lt_i32 s11, 0x8000
	s_cselect_b32 s46, s11, s46
	s_cselect_b32 s11, s13, 0
	s_add_u32 s34, s34, s11
	s_addc_u32 s35, s35, 0
	s_waitcnt vmcnt(4)
	v_lshlrev_b32_e32 v54, 16, v100
	v_and_b32_e32 v55, 0xffff0000, v100
	v_lshlrev_b32_e32 v56, 16, v101
	v_and_b32_e32 v57, 0xffff0000, v101
	v_lshlrev_b32_e32 v58, 16, v102
	v_and_b32_e32 v59, 0xffff0000, v102
	v_lshlrev_b32_e32 v60, 16, v103
	v_and_b32_e32 v61, 0xffff0000, v103
	v_lshlrev_b32_e32 v62, 16, v104
	v_and_b32_e32 v63, 0xffff0000, v104
	v_lshlrev_b32_e32 v64, 16, v105
	v_and_b32_e32 v65, 0xffff0000, v105
	v_lshlrev_b32_e32 v66, 16, v106
	v_and_b32_e32 v67, 0xffff0000, v106
	v_lshlrev_b32_e32 v68, 16, v107
	v_and_b32_e32 v69, 0xffff0000, v107
.Lnf_loopA:
	global_load_dwordx2 v[100:101], v86, s[34:35]
	global_load_dwordx2 v[102:103], v86, s[34:35] offset:512
	global_load_dwordx2 v[104:105], v86, s[34:35] offset:1024
	global_load_dwordx2 v[106:107], v86, s[34:35] offset:1536
	s_add_i32 s11, s46, s12
	s_cmp_lt_i32 s11, 0x8000
	s_cselect_b32 s46, s11, s46
	s_cselect_b32 s11, s13, 0
	s_add_u32 s34, s34, s11
	s_addc_u32 s35, s35, 0
	v_pk_mul_f32 v[90:91], v[56:57], v[56:57]
	v_pk_mul_f32 v[92:93], v[54:55], v[54:55]
	v_pk_mul_f32 v[4:5], v[60:61], v[60:61]
	v_pk_mul_f32 v[88:89], v[58:59], v[58:59]
	v_pk_mov_b32 v[94:95], v[92:93], v[90:91] op_sel:[1,0]
	v_mov_b32_e32 v93, v91
	v_pk_add_f32 v[90:91], v[94:95], v[92:93]
	v_pk_mov_b32 v[92:93], v[88:89], v[4:5] op_sel:[1,0]
	v_mov_b32_e32 v89, v5
	v_pk_add_f32 v[4:5], v[92:93], v[88:89]
	v_pk_add_f32 v[90:91], v[90:91], v[90:91] op_sel_hi:[0,1]
	v_pk_add_f32 v[4:5], v[4:5], v[4:5] op_sel_hi:[0,1]
	v_mul_f32_e32 v4, v62, v62
	v_pk_fma_f32 v[88:89], v[62:63], v[62:63], v[4:5] op_sel_hi:[1,1,0]
	v_mul_f32_e32 v4, v64, v64
	v_pk_fma_f32 v[92:93], v[64:65], v[64:65], v[4:5] op_sel_hi:[1,1,0]
	v_mul_f32_e32 v88, v66, v66
	v_mul_f32_e32 v92, v67, v67
	v_mul_f32_e32 v90, v68, v68
	v_mul_f32_e32 v4, v69, v69
	v_pk_add_f32 v[88:89], v[88:89], v[92:93]
	v_pk_add_f32 v[4:5], v[90:91], v[4:5]
	v_pk_add_f32 v[4:5], v[88:89], v[4:5]
	s_nop 0
	v_add_f32_e32 v3, v4, v5
	ds_bpermute_b32 v4, v1, v3
	s_waitcnt lgkmcnt(0)
	v_add_f32_e32 v3, v3, v4
	ds_bpermute_b32 v4, v71, v3
	s_waitcnt lgkmcnt(0)
	v_add_f32_e32 v3, v3, v4
	ds_bpermute_b32 v4, v73, v3
	s_waitcnt lgkmcnt(0)
	v_add_f32_e32 v3, v3, v4
	ds_bpermute_b32 v4, v96, v3
	s_waitcnt lgkmcnt(0)
	v_add_f32_e32 v3, v3, v4
	ds_bpermute_b32 v4, v97, v3
	s_waitcnt lgkmcnt(0)
	v_add_f32_e32 v3, v3, v4
	ds_bpermute_b32 v4, v98, v3
	s_waitcnt lgkmcnt(0)
	v_add_f32_e32 v3, v3, v4
	v_fmamk_f32 v3, v3, 0x3a800000, v238
	v_mul_f32_e32 v4, 0x4f800000, v3
	v_cmp_gt_f32_e32 vcc, s58, v3
	s_nop 1
	v_cndmask_b32_e32 v3, v3, v4, vcc
	v_sqrt_f32_e32 v4, v3
	s_nop 0
	v_add_u32_e32 v5, -1, v4
	v_add_u32_e32 v75, 1, v4
	v_fma_f32 v88, -v5, v4, v3
	v_fma_f32 v89, -v75, v4, v3
	v_cmp_ge_f32_e64 s[4:5], 0, v88
	s_nop 1
	v_cndmask_b32_e64 v4, v4, v5, s[4:5]
	v_cmp_lt_f32_e64 s[4:5], 0, v89
	s_nop 1
	v_cndmask_b32_e64 v4, v4, v75, s[4:5]
	v_mul_f32_e32 v5, 0x37800000, v4
	v_cndmask_b32_e32 v4, v4, v5, vcc
	v_cmp_class_f32_e32 vcc, v3, v248
	s_nop 1
	v_cndmask_b32_e32 v3, v4, v3, vcc
	v_div_scale_f32 v75, s[4:5], v3, v3, 1.0
	v_rcp_f32_e32 v88, v75
	v_div_scale_f32 v89, vcc, 1.0, v3, 1.0
	v_fma_f32 v90, -v75, v88, 1.0
	v_fmac_f32_e32 v88, v90, v88
	v_mul_f32_e32 v90, v89, v88
	v_fma_f32 v91, -v75, v90, v89
	v_fmac_f32_e32 v90, v91, v88
	v_fma_f32 v75, -v75, v90, v89
	v_div_fmas_f32 v75, v75, v88, v90
	v_div_fixup_f32 v88, v75, v3, 1.0
	s_waitcnt vmcnt(4)
	v_pk_mul_f32 v[54:55], v[54:55], v[88:89] op_sel_hi:[1,0]
	v_pk_mul_f32 v[56:57], v[56:57], v[88:89] op_sel_hi:[1,0]
	v_pk_mul_f32 v[54:55], v[54:55], v[6:7]
	v_pk_mul_f32 v[56:57], v[56:57], v[8:9]
	global_store_dwordx4 v74, v[54:57], s[36:37]
	v_pk_mul_f32 v[58:59], v[58:59], v[88:89] op_sel_hi:[1,0]
	v_pk_mul_f32 v[60:61], v[60:61], v[88:89] op_sel_hi:[1,0]
	v_pk_mul_f32 v[58:59], v[58:59], v[14:15]
	v_pk_mul_f32 v[60:61], v[60:61], v[16:17]
	global_store_dwordx4 v74, v[58:61], s[36:37] offset:1024
	v_pk_mul_f32 v[62:63], v[62:63], v[88:89] op_sel_hi:[1,0]
	v_pk_mul_f32 v[64:65], v[64:65], v[88:89] op_sel_hi:[1,0]
	v_pk_mul_f32 v[62:63], v[62:63], v[26:27]
	v_pk_mul_f32 v[64:65], v[64:65], v[28:29]
	global_store_dwordx4 v74, v[62:65], s[36:37] offset:2048
	v_pk_mul_f32 v[66:67], v[66:67], v[88:89] op_sel_hi:[1,0]
	v_pk_mul_f32 v[68:69], v[68:69], v[88:89] op_sel_hi:[1,0]
	v_pk_mul_f32 v[66:67], v[66:67], v[38:39]
	v_pk_mul_f32 v[68:69], v[68:69], v[40:41]
	global_store_dwordx4 v74, v[66:69], s[36:37] offset:3072
	s_nop 1
	v_lshlrev_b32_e32 v54, 16, v108
	v_and_b32_e32 v55, 0xffff0000, v108
	v_lshlrev_b32_e32 v56, 16, v109
	v_and_b32_e32 v57, 0xffff0000, v109
	v_lshlrev_b32_e32 v58, 16, v110
	v_and_b32_e32 v59, 0xffff0000, v110
	v_lshlrev_b32_e32 v60, 16, v111
	v_and_b32_e32 v61, 0xffff0000, v111
	v_lshlrev_b32_e32 v62, 16, v112
	v_and_b32_e32 v63, 0xffff0000, v112
	v_lshlrev_b32_e32 v64, 16, v113
	v_and_b32_e32 v65, 0xffff0000, v113
	v_lshlrev_b32_e32 v66, 16, v114
	v_and_b32_e32 v67, 0xffff0000, v114
	v_lshlrev_b32_e32 v68, 16, v115
	v_and_b32_e32 v69, 0xffff0000, v115
	s_add_i32 s8, s8, s12
	s_add_u32 s36, s36, s3
	s_addc_u32 s37, s37, 0
	s_cmp_lt_i32 s8, 0x8000
	s_cbranch_scc0 .Lnf_done
; __global__ void __launch_bounds__(NTHR, 2) mk_fwd(Args a) {
;     ...
;                     for (int row = gw; row < ML; row += NGW) {
;                         f32x4* xr = (f32x4*)(xres + (size_t)row * DM); f32x4 v[4]; float s = 0.f;
; #pragma unroll
;                         for (int j = 0; j < 4; ++j) { v[j] = ld_row4(nullptr, XB, nullptr, row, lane + 64 * j); s += (v[j].x * v[j].x + v[j].y * v[j].y) + (v[j].z * v[j].z + v[j].w * v[j].w); }
;                         s = wave_sum(s, lane); const float rstd = 1.0f / sqrtf(s * (1.0f / DM) + 1e-6f);
; #pragma unroll
;                         for (int j = 0; j < 4; ++j) xr[lane + 64 * j] = v[j] * rstd * ((const f32x4*)final_g)[lane + 64 * j];
;                     }
.Lnf_loopB:
	global_load_dwordx2 v[108:109], v86, s[34:35]
	global_load_dwordx2 v[110:111], v86, s[34:35] offset:512
	global_load_dwordx2 v[112:113], v86, s[34:35] offset:1024
	global_load_dwordx2 v[114:115], v86, s[34:35] offset:1536
	s_add_i32 s11, s46, s12
	s_cmp_lt_i32 s11, 0x8000
	s_cselect_b32 s46, s11, s46
	s_cselect_b32 s11, s13, 0
	s_add_u32 s34, s34, s11
	s_addc_u32 s35, s35, 0
	v_pk_mul_f32 v[90:91], v[56:57], v[56:57]
	v_pk_mul_f32 v[92:93], v[54:55], v[54:55]
	v_pk_mul_f32 v[4:5], v[60:61], v[60:61]
	v_pk_mul_f32 v[88:89], v[58:59], v[58:59]
	v_pk_mov_b32 v[94:95], v[92:93], v[90:91] op_sel:[1,0]
	v_mov_b32_e32 v93, v91
	v_pk_add_f32 v[90:91], v[94:95], v[92:93]
	v_pk_mov_b32 v[92:93], v[88:89], v[4:5] op_sel:[1,0]
	v_mov_b32_e32 v89, v5
	v_pk_add_f32 v[4:5], v[92:93], v[88:89]
	v_pk_add_f32 v[90:91], v[90:91], v[90:91] op_sel_hi:[0,1]
	v_pk_add_f32 v[4:5], v[4:5], v[4:5] op_sel_hi:[0,1]
	v_mul_f32_e32 v4, v62, v62
	v_pk_fma_f32 v[88:89], v[62:63], v[62:63], v[4:5] op_sel_hi:[1,1,0]
	v_mul_f32_e32 v4, v64, v64
	v_pk_fma_f32 v[92:93], v[64:65], v[64:65], v[4:5] op_sel_hi:[1,1,0]
	v_mul_f32_e32 v88, v66, v66
	v_mul_f32_e32 v92, v67, v67
	v_mul_f32_e32 v90, v68, v68
	v_mul_f32_e32 v4, v69, v69
	v_pk_add_f32 v[88:89], v[88:89], v[92:93]
	v_pk_add_f32 v[4:5], v[90:91], v[4:5]
	v_pk_add_f32 v[4:5], v[88:89], v[4:5]
	s_nop 0
	v_add_f32_e32 v3, v4, v5
	ds_bpermute_b32 v4, v1, v3
	s_waitcnt lgkmcnt(0)
	v_add_f32_e32 v3, v3, v4
	ds_bpermute_b32 v4, v71, v3
	s_waitcnt lgkmcnt(0)
	v_add_f32_e32 v3, v3, v4
	ds_bpermute_b32 v4, v73, v3
	s_waitcnt lgkmcnt(0)
	v_add_f32_e32 v3, v3, v4
	ds_bpermute_b32 v4, v96, v3
	s_waitcnt lgkmcnt(0)
	v_add_f32_e32 v3, v3, v4
	ds_bpermute_b32 v4, v97, v3
	s_waitcnt lgkmcnt(0)
	v_add_f32_e32 v3, v3, v4
	ds_bpermute_b32 v4, v98, v3
	s_waitcnt lgkmcnt(0)
	v_add_f32_e32 v3, v3, v4
	v_fmamk_f32 v3, v3, 0x3a800000, v238
	v_mul_f32_e32 v4, 0x4f800000, v3
	v_cmp_gt_f32_e32 vcc, s58, v3
	s_nop 1
	v_cndmask_b32_e32 v3, v3, v4, vcc
	v_sqrt_f32_e32 v4, v3
	s_nop 0
	v_add_u32_e32 v5, -1, v4
	v_add_u32_e32 v75, 1, v4
	v_fma_f32 v88, -v5, v4, v3
	v_fma_f32 v89, -v75, v4, v3
	v_cmp_ge_f32_e64 s[4:5], 0, v88
	s_nop 1
	v_cndmask_b32_e64 v4, v4, v5, s[4:5]
	v_cmp_lt_f32_e64 s[4:5], 0, v89
	s_nop 1
	v_cndmask_b32_e64 v4, v4, v75, s[4:5]
	v_mul_f32_e32 v5, 0x37800000, v4
	v_cndmask_b32_e32 v4, v4, v5, vcc
	v_cmp_class_f32_e32 vcc, v3, v248
	s_nop 1
	v_cndmask_b32_e32 v3, v4, v3, vcc
	v_div_scale_f32 v75, s[4:5], v3, v3, 1.0
	v_rcp_f32_e32 v88, v75
	v_div_scale_f32 v89, vcc, 1.0, v3, 1.0
	v_fma_f32 v90, -v75, v88, 1.0
	v_fmac_f32_e32 v88, v90, v88
	v_mul_f32_e32 v90, v89, v88
	v_fma_f32 v91, -v75, v90, v89
	v_fmac_f32_e32 v90, v91, v88
	v_fma_f32 v75, -v75, v90, v89
	v_div_fmas_f32 v75, v75, v88, v90
	v_div_fixup_f32 v88, v75, v3, 1.0
	s_waitcnt vmcnt(4)
	v_pk_mul_f32 v[54:55], v[54:55], v[88:89] op_sel_hi:[1,0]
	v_pk_mul_f32 v[56:57], v[56:57], v[88:89] op_sel_hi:[1,0]
	v_pk_mul_f32 v[54:55], v[54:55], v[6:7]
	v_pk_mul_f32 v[56:57], v[56:57], v[8:9]
	global_store_dwordx4 v74, v[54:57], s[36:37]
	v_pk_mul_f32 v[58:59], v[58:59], v[88:89] op_sel_hi:[1,0]
	v_pk_mul_f32 v[60:61], v[60:61], v[88:89] op_sel_hi:[1,0]
	v_pk_mul_f32 v[58:59], v[58:59], v[14:15]
	v_pk_mul_f32 v[60:61], v[60:61], v[16:17]
	global_store_dwordx4 v74, v[58:61], s[36:37] offset:1024
	v_pk_mul_f32 v[62:63], v[62:63], v[88:89] op_sel_hi:[1,0]
	v_pk_mul_f32 v[64:65], v[64:65], v[88:89] op_sel_hi:[1,0]
	v_pk_mul_f32 v[62:63], v[62:63], v[26:27]
	v_pk_mul_f32 v[64:65], v[64:65], v[28:29]
	global_store_dwordx4 v74, v[62:65], s[36:37] offset:2048
	v_pk_mul_f32 v[66:67], v[66:67], v[88:89] op_sel_hi:[1,0]
	v_pk_mul_f32 v[68:69], v[68:69], v[88:89] op_sel_hi:[1,0]
	v_pk_mul_f32 v[66:67], v[66:67], v[38:39]
	v_pk_mul_f32 v[68:69], v[68:69], v[40:41]
	global_store_dwordx4 v74, v[66:69], s[36:37] offset:3072
	s_nop 1
	v_lshlrev_b32_e32 v54, 16, v100
	v_and_b32_e32 v55, 0xffff0000, v100
	v_lshlrev_b32_e32 v56, 16, v101
	v_and_b32_e32 v57, 0xffff0000, v101
	v_lshlrev_b32_e32 v58, 16, v102
	v_and_b32_e32 v59, 0xffff0000, v102
	v_lshlrev_b32_e32 v60, 16, v103
	v_and_b32_e32 v61, 0xffff0000, v103
	v_lshlrev_b32_e32 v62, 16, v104
	v_and_b32_e32 v63, 0xffff0000, v104
	v_lshlrev_b32_e32 v64, 16, v105
	v_and_b32_e32 v65, 0xffff0000, v105
	v_lshlrev_b32_e32 v66, 16, v106
	v_and_b32_e32 v67, 0xffff0000, v106
	v_lshlrev_b32_e32 v68, 16, v107
	v_and_b32_e32 v69, 0xffff0000, v107
	s_add_i32 s8, s8, s12
	s_add_u32 s36, s36, s3
	s_addc_u32 s37, s37, 0
	s_cmp_lt_i32 s8, 0x8000
	s_cbranch_scc0 .Lnf_done
	s_branch .Lnf_loopA
.Lnf_done:
	s_mov_b32 s59, 0x615c000

; #define LAS __attribute__((address_space(3)))
; __device__ __forceinline__ void stage_z(const bf16_t* U, int tok0, int stride, int col_r, int col_i, LAS unsigned char* tile, int lane) {
;     ...
;     for (int it = 0; it < 16; ++it) { const int idx = it * 64 + lane, row = idx >> 3, piece = (idx >> 2) & 1, chunk = idx & 3;
;         v[it] = *(const u32x4*)(U + (size_t)(tok0 + stride * row) * NU + (piece ? col_i : col_r) + 8 * chunk); }
; #pragma unroll
;     for (int it = 0; it < 16; ++it) { const int idx = it * 64 + lane, row = idx >> 3, piece = (idx >> 2) & 1, chunk = idx & 3;
;         *(LAS u32x4*)(tile + row * 128 + ((piece ^ ((row >> 1) & 1)) * 64) + chunk * 16) = v[it]; }
; __device__ __forceinline__ void dft1_mfma(const bf16_t* U, bf16_t* YB, const bf16_t* A1, const float* TW, LAS unsigned char* tile, int gw, int NGW, int lane) {
;     ...
;             const bf16_t* ap = A1 + (size_t)(32 * mb + r32) * 256 + 8 * hh;
; #pragma unroll
;             for (int kk = 0; kk < 8; ++kk) {
;                 const bf16x8 ac = *(const bf16x8*)(ap + 16 * kk), as = *(const bf16x8*)(ap + 128 + 16 * kk);
;                 const bf16x8 br = tr2(tile + offR + kk * 2048, 512), bi = tr2(tile + offI + kk * 2048, 512);
;                 aR = __builtin_amdgcn_mfma_f32_32x32x16_bf16(ac, br, aR, 0, 0, 0); aR = __builtin_amdgcn_mfma_f32_32x32x16_bf16(as, bi, aR, 0, 0, 0);
;                 aI = __builtin_amdgcn_mfma_f32_32x32x16_bf16(ac, bi, aI, 0, 0, 0); aI = __builtin_amdgcn_mfma_f32_32x32x16_bf16(negbf(as), br, aI, 0, 0, 0);
;             }
; #pragma unroll
;             for (int i = 0; i < 16; ++i) { const int ka = 32 * mb + 8 * (i >> 2) + 4 * hh + (i & 3); const float tc = TW[ka * 64 + sf], ts = TW[8192 + ka * 64 + sf];
.LBB0_697:
	s_and_b32 s3, s15, 0x180
	s_and_b32 s6, s13, 32
	v_add_u32_e32 v4, s3, v80
	s_bfe_u32 s18, s10, 0x60003
	s_and_b32 s0, s2, 0xffffe000
	v_or_b32_e32 v4, s6, v4
	s_or_b32 s17, s0, s18
	v_lshlrev_b32_e32 v4, 1, v4
	v_mov_b32_e32 v5, v2
	v_lshl_add_u64 v[172:173], v[0:1], 0, v[4:5]
	v_or_b32_e32 v75, s17, v3
	v_mad_i64_i32 v[4:5], s[0:1], v75, s50, v[172:173]
	v_or_b32_e32 v8, 0x200, v75
	global_load_dwordx4 v[4:7], v[4:5], off
	v_mad_i64_i32 v[8:9], s[0:1], v8, s50, v[172:173]
	v_or_b32_e32 v12, 0x400, v75
	global_load_dwordx4 v[8:11], v[8:9], off
	v_mad_i64_i32 v[12:13], s[0:1], v12, s50, v[172:173]
	v_or_b32_e32 v16, 0x600, v75
	global_load_dwordx4 v[12:15], v[12:13], off
	v_mad_i64_i32 v[16:17], s[0:1], v16, s50, v[172:173]
	v_or_b32_e32 v20, 0x800, v75
	global_load_dwordx4 v[16:19], v[16:17], off
	v_mad_i64_i32 v[20:21], s[0:1], v20, s50, v[172:173]
	v_or_b32_e32 v24, 0xa00, v75
	global_load_dwordx4 v[20:23], v[20:21], off
	v_mad_i64_i32 v[24:25], s[0:1], v24, s50, v[172:173]
	v_or_b32_e32 v28, 0xc00, v75
	global_load_dwordx4 v[24:27], v[24:25], off
	v_mad_i64_i32 v[28:29], s[0:1], v28, s50, v[172:173]
	v_or_b32_e32 v32, 0xe00, v75
	global_load_dwordx4 v[28:31], v[28:29], off
	v_mad_i64_i32 v[32:33], s[0:1], v32, s50, v[172:173]
	v_or_b32_e32 v76, 0x1000, v75
	global_load_dwordx4 v[32:35], v[32:33], off
	v_mad_i64_i32 v[76:77], s[0:1], v76, s50, v[172:173]
	v_or_b32_e32 v148, 0x1200, v75
	global_load_dwordx4 v[76:79], v[76:77], off
	v_mad_i64_i32 v[148:149], s[0:1], v148, s50, v[172:173]
	v_or_b32_e32 v152, 0x1400, v75
	global_load_dwordx4 v[148:151], v[148:149], off
	v_mad_i64_i32 v[152:153], s[0:1], v152, s50, v[172:173]
	v_or_b32_e32 v156, 0x1600, v75
	global_load_dwordx4 v[152:155], v[152:153], off
	v_mad_i64_i32 v[156:157], s[0:1], v156, s50, v[172:173]
	v_or_b32_e32 v160, 0x1800, v75
	global_load_dwordx4 v[156:159], v[156:157], off
	v_mad_i64_i32 v[160:161], s[0:1], v160, s50, v[172:173]
	v_or_b32_e32 v164, 0x1a00, v75
	global_load_dwordx4 v[160:163], v[160:161], off
	v_mad_i64_i32 v[164:165], s[0:1], v164, s50, v[172:173]
	v_or_b32_e32 v168, 0x1c00, v75
	global_load_dwordx4 v[164:167], v[164:165], off
	v_mad_i64_i32 v[168:169], s[0:1], v168, s50, v[172:173]
	v_or_b32_e32 v75, 0x1e00, v75
	global_load_dwordx4 v[168:171], v[168:169], off
	v_mad_i64_i32 v[172:173], s[0:1], v75, s50, v[172:173]
	global_load_dwordx4 v[172:175], v[172:173], off
	s_lshl_b32 s0, s3, 1
	s_add_u32 s0, s20, s0
	s_addc_u32 s1, s21, 0
	s_lshl_b32 s3, s6, 1
	s_add_u32 s6, s0, s3
	s_addc_u32 s7, s1, 0
	v_mov_b32_e32 v75, v2
	s_add_i32 s10, s10, s12
	s_add_i32 s13, s13, s14
	s_add_i32 s15, s15, s11
	s_add_i32 s2, s2, s16
	s_cmpk_gt_i32 s10, 0x7ff
	s_waitcnt vmcnt(0) lgkmcnt(0)
	ds_write_b128 v145, v[4:7]
	ds_write_b128 v145, v[8:11] offset:1024
	ds_write_b128 v145, v[12:15] offset:2048
	ds_write_b128 v145, v[16:19] offset:3072
	ds_write_b128 v145, v[20:23] offset:4096
	ds_write_b128 v145, v[24:27] offset:5120
	ds_write_b128 v145, v[28:31] offset:6144
	ds_write_b128 v145, v[32:35] offset:7168
	ds_write_b128 v145, v[76:79] offset:8192
	ds_write_b128 v145, v[148:151] offset:9216
	ds_write_b128 v145, v[152:155] offset:10240
	ds_write_b128 v145, v[156:159] offset:11264
	ds_write_b128 v145, v[160:163] offset:12288
	ds_write_b128 v145, v[164:167] offset:13312
	ds_write_b128 v145, v[168:171] offset:14336
	ds_write_b128 v145, v[172:175] offset:15360
	s_waitcnt lgkmcnt(0)
	v_or_b32_e32 v229, s18, v81
	v_lshlrev_b32_e32 v229, 2, v229
	global_load_dwordx4 v[84:87], v[36:37], off
	global_load_dwordx4 v[88:91], v[36:37], off offset:256
	global_load_dwordx4 v[92:95], v[36:37], off offset:32
	global_load_dwordx4 v[96:99], v[36:37], off offset:288
	global_load_dwordx4 v[100:103], v[36:37], off offset:64
	global_load_dwordx4 v[104:107], v[36:37], off offset:320
	global_load_dwordx4 v[108:111], v[36:37], off offset:96
	global_load_dwordx4 v[112:115], v[36:37], off offset:352
	global_load_dwordx4 v[116:119], v[36:37], off offset:128
	global_load_dwordx4 v[120:123], v[36:37], off offset:384
	global_load_dwordx4 v[124:127], v[36:37], off offset:160
	global_load_dwordx4 v[128:131], v[36:37], off offset:416
	global_load_dwordx4 v[132:135], v[36:37], off offset:192
	global_load_dwordx4 v[136:139], v[36:37], off offset:448
	global_load_dwordx4 v[140:143], v[36:37], off offset:224
	global_load_dwordx4 v[60:63], v[36:37], off offset:480
	v_or_b32_e32 v231, 0x0, v229
	v_add_u32_e32 v232, 0x8000, v231
	global_load_dword v42, v231, s[4:5]
	global_load_dword v213, v232, s[4:5]
	v_or_b32_e32 v231, 0x100, v229
	v_add_u32_e32 v232, 0x8000, v231
	global_load_dword v43, v231, s[4:5]
	global_load_dword v214, v232, s[4:5]
	v_or_b32_e32 v231, 0x200, v229
	v_add_u32_e32 v232, 0x8000, v231
	global_load_dword v44, v231, s[4:5]
	global_load_dword v215, v232, s[4:5]
	v_or_b32_e32 v231, 0x300, v229
	v_add_u32_e32 v232, 0x8000, v231
	global_load_dword v45, v231, s[4:5]
	global_load_dword v216, v232, s[4:5]
	v_or_b32_e32 v231, 0x800, v229
	v_add_u32_e32 v232, 0x8000, v231
	global_load_dword v46, v231, s[4:5]
	global_load_dword v217, v232, s[4:5]
	v_or_b32_e32 v231, 0x900, v229
	v_add_u32_e32 v232, 0x8000, v231
	global_load_dword v47, v231, s[4:5]
	global_load_dword v218, v232, s[4:5]
	v_or_b32_e32 v231, 0xa00, v229
	v_add_u32_e32 v232, 0x8000, v231
	global_load_dword v48, v231, s[4:5]
	global_load_dword v219, v232, s[4:5]
	v_or_b32_e32 v231, 0xb00, v229
	v_add_u32_e32 v232, 0x8000, v231
	global_load_dword v49, v231, s[4:5]
	global_load_dword v220, v232, s[4:5]
	v_or_b32_e32 v231, 0x1000, v229
	v_add_u32_e32 v232, 0x8000, v231
	global_load_dword v50, v231, s[4:5]
	global_load_dword v221, v232, s[4:5]
; __device__ __forceinline__ void dft1_mfma(const bf16_t* U, bf16_t* YB, const bf16_t* A1, const float* TW, LAS unsigned char* tile, int gw, int NGW, int lane) {
;     ...
;             const bf16_t* ap = A1 + (size_t)(32 * mb + r32) * 256 + 8 * hh;
; #pragma unroll
;             for (int kk = 0; kk < 8; ++kk) {
;                 const bf16x8 ac = *(const bf16x8*)(ap + 16 * kk), as = *(const bf16x8*)(ap + 128 + 16 * kk);
;                 const bf16x8 br = tr2(tile + offR + kk * 2048, 512), bi = tr2(tile + offI + kk * 2048, 512);
;                 aR = __builtin_amdgcn_mfma_f32_32x32x16_bf16(ac, br, aR, 0, 0, 0); aR = __builtin_amdgcn_mfma_f32_32x32x16_bf16(as, bi, aR, 0, 0, 0);
;                 aI = __builtin_amdgcn_mfma_f32_32x32x16_bf16(ac, bi, aI, 0, 0, 0); aI = __builtin_amdgcn_mfma_f32_32x32x16_bf16(negbf(as), br, aI, 0, 0, 0);
	v_or_b32_e32 v231, 0x1100, v229
	v_add_u32_e32 v232, 0x8000, v231
	global_load_dword v51, v231, s[4:5]
	global_load_dword v222, v232, s[4:5]
	v_or_b32_e32 v231, 0x1200, v229
	v_add_u32_e32 v232, 0x8000, v231
	global_load_dword v52, v231, s[4:5]
	global_load_dword v223, v232, s[4:5]
	v_or_b32_e32 v231, 0x1300, v229
	v_add_u32_e32 v232, 0x8000, v231
	global_load_dword v53, v231, s[4:5]
	global_load_dword v224, v232, s[4:5]
	v_or_b32_e32 v231, 0x1800, v229
	v_add_u32_e32 v232, 0x8000, v231
	global_load_dword v54, v231, s[4:5]
	global_load_dword v225, v232, s[4:5]
	v_or_b32_e32 v231, 0x1900, v229
	v_add_u32_e32 v232, 0x8000, v231
	global_load_dword v55, v231, s[4:5]
	global_load_dword v226, v232, s[4:5]
	v_or_b32_e32 v231, 0x1a00, v229
	v_add_u32_e32 v232, 0x8000, v231
	global_load_dword v56, v231, s[4:5]
	global_load_dword v227, v232, s[4:5]
	v_or_b32_e32 v231, 0x1b00, v229
	v_add_u32_e32 v232, 0x8000, v231
	global_load_dword v57, v231, s[4:5]
	global_load_dword v228, v232, s[4:5]
	ds_read_b64_tr_b16 v[148:149], v146
	ds_read_b64_tr_b16 v[150:151], v146 offset:512
	ds_read_b64_tr_b16 v[152:153], v147
	ds_read_b64_tr_b16 v[154:155], v147 offset:512
	ds_read_b64_tr_b16 v[156:157], v146 offset:2048
	ds_read_b64_tr_b16 v[158:159], v146 offset:2560
	ds_read_b64_tr_b16 v[160:161], v147 offset:2048
	ds_read_b64_tr_b16 v[162:163], v147 offset:2560
	ds_read_b64_tr_b16 v[164:165], v146 offset:4096
	ds_read_b64_tr_b16 v[166:167], v146 offset:4608
	ds_read_b64_tr_b16 v[168:169], v147 offset:4096
	ds_read_b64_tr_b16 v[170:171], v147 offset:4608
	ds_read_b64_tr_b16 v[172:173], v146 offset:6144
	ds_read_b64_tr_b16 v[174:175], v146 offset:6656
	ds_read_b64_tr_b16 v[176:177], v147 offset:6144
	ds_read_b64_tr_b16 v[178:179], v147 offset:6656
	ds_read_b64_tr_b16 v[180:181], v146 offset:8192
	ds_read_b64_tr_b16 v[182:183], v146 offset:8704
	ds_read_b64_tr_b16 v[184:185], v147 offset:8192
	ds_read_b64_tr_b16 v[186:187], v147 offset:8704
	ds_read_b64_tr_b16 v[188:189], v146 offset:10240
	ds_read_b64_tr_b16 v[190:191], v146 offset:10752
	ds_read_b64_tr_b16 v[192:193], v147 offset:10240
	ds_read_b64_tr_b16 v[194:195], v147 offset:10752
	ds_read_b64_tr_b16 v[196:197], v146 offset:12288
	ds_read_b64_tr_b16 v[198:199], v146 offset:12800
	ds_read_b64_tr_b16 v[200:201], v147 offset:12288
	ds_read_b64_tr_b16 v[202:203], v147 offset:12800
	ds_read_b64_tr_b16 v[204:205], v146 offset:14336
	ds_read_b64_tr_b16 v[206:207], v146 offset:14848
	ds_read_b64_tr_b16 v[64:65], v147 offset:14336
	ds_read_b64_tr_b16 v[66:67], v147 offset:14848
	v_lshlrev_b32_e64 v237, 14, s74
	v_lshlrev_b32_e32 v239, 4, v249
	v_add_u32_e32 v239, v237, v239
	v_and_b32_e32 v231, 32, v249
	v_lshlrev_b32_e32 v231, 4, v231
	v_add3_u32 v237, v237, v231, v74
	v_lshlrev_b32_e64 v233, 10, s17
	v_lshrrev_b32_e32 v231, 3, v249
	v_lshl_add_u32 v233, v231, 16, v233
	v_and_b32_e32 v231, 7, v249
	v_lshl_add_u32 v233, v231, 4, v233
	v_and_b32_e32 v231, 4, v249
	v_lshl_add_u32 v233, v231, 4, v233
	s_waitcnt lgkmcnt(0)
	s_waitcnt vmcnt(32)
	v_mfma_f32_32x32x16_bf16 v[4:19], v[84:87], v[148:151], 0
	v_mfma_f32_32x32x16_bf16 v[4:19], v[88:91], v[152:155], v[4:19]
	v_xor_b32_e32 v68, 0x80008000, v88
	v_xor_b32_e32 v69, 0x80008000, v89
	v_xor_b32_e32 v70, 0x80008000, v90
	v_xor_b32_e32 v71, 0x80008000, v91
	v_mfma_f32_32x32x16_bf16 v[20:35], v[84:87], v[152:155], 0
	s_nop 0
	v_mfma_f32_32x32x16_bf16 v[20:35], v[68:71], v[148:151], v[20:35]
	v_mfma_f32_32x32x16_bf16 v[4:19], v[92:95], v[156:159], v[4:19]
	v_mfma_f32_32x32x16_bf16 v[4:19], v[96:99], v[160:163], v[4:19]
	v_xor_b32_e32 v68, 0x80008000, v96
	v_xor_b32_e32 v69, 0x80008000, v97
	v_xor_b32_e32 v70, 0x80008000, v98
	v_xor_b32_e32 v71, 0x80008000, v99
	v_mfma_f32_32x32x16_bf16 v[20:35], v[92:95], v[160:163], v[20:35]
	s_nop 0
	v_mfma_f32_32x32x16_bf16 v[20:35], v[68:71], v[156:159], v[20:35]
	v_mfma_f32_32x32x16_bf16 v[4:19], v[100:103], v[164:167], v[4:19]
	v_mfma_f32_32x32x16_bf16 v[4:19], v[104:107], v[168:171], v[4:19]
	v_xor_b32_e32 v68, 0x80008000, v104
	v_xor_b32_e32 v69, 0x80008000, v105
	v_xor_b32_e32 v70, 0x80008000, v106
	v_xor_b32_e32 v71, 0x80008000, v107
	v_mfma_f32_32x32x16_bf16 v[20:35], v[100:103], v[168:171], v[20:35]
	s_nop 0
	v_mfma_f32_32x32x16_bf16 v[20:35], v[68:71], v[164:167], v[20:35]
	v_mfma_f32_32x32x16_bf16 v[4:19], v[108:111], v[172:175], v[4:19]
	v_mfma_f32_32x32x16_bf16 v[4:19], v[112:115], v[176:179], v[4:19]
	v_xor_b32_e32 v68, 0x80008000, v112
	v_xor_b32_e32 v69, 0x80008000, v113
	v_xor_b32_e32 v70, 0x80008000, v114
	v_xor_b32_e32 v71, 0x80008000, v115
	v_mfma_f32_32x32x16_bf16 v[20:35], v[108:111], v[176:179], v[20:35]
	s_nop 0
	v_mfma_f32_32x32x16_bf16 v[20:35], v[68:71], v[172:175], v[20:35]
	v_mfma_f32_32x32x16_bf16 v[4:19], v[116:119], v[180:183], v[4:19]
	v_mfma_f32_32x32x16_bf16 v[4:19], v[120:123], v[184:187], v[4:19]
	v_xor_b32_e32 v68, 0x80008000, v120
	v_xor_b32_e32 v69, 0x80008000, v121
	v_xor_b32_e32 v70, 0x80008000, v122
	v_xor_b32_e32 v71, 0x80008000, v123
	v_mfma_f32_32x32x16_bf16 v[20:35], v[116:119], v[184:187], v[20:35]
	s_nop 0
	v_mfma_f32_32x32x16_bf16 v[20:35], v[68:71], v[180:183], v[20:35]
	v_mfma_f32_32x32x16_bf16 v[4:19], v[124:127], v[188:191], v[4:19]
	v_mfma_f32_32x32x16_bf16 v[4:19], v[128:131], v[192:195], v[4:19]
	v_xor_b32_e32 v68, 0x80008000, v128
	v_xor_b32_e32 v69, 0x80008000, v129
	v_xor_b32_e32 v70, 0x80008000, v130
	v_xor_b32_e32 v71, 0x80008000, v131
	v_mfma_f32_32x32x16_bf16 v[20:35], v[124:127], v[192:195], v[20:35]
	s_nop 0
	v_mfma_f32_32x32x16_bf16 v[20:35], v[68:71], v[188:191], v[20:35]
	v_mfma_f32_32x32x16_bf16 v[4:19], v[132:135], v[196:199], v[4:19]
; __device__ __forceinline__ bf16_t bf1(float v) { return (bf16_t)pk2(v, 0.f); }
; __device__ __forceinline__ void dft1_mfma(const bf16_t* U, bf16_t* YB, const bf16_t* A1, const float* TW, LAS unsigned char* tile, int gw, int NGW, int lane) {
;     ...
;             const bf16_t* ap = A1 + (size_t)(32 * mb + r32) * 256 + 8 * hh;
; #pragma unroll
;             for (int kk = 0; kk < 8; ++kk) {
;                 const bf16x8 ac = *(const bf16x8*)(ap + 16 * kk), as = *(const bf16x8*)(ap + 128 + 16 * kk);
;                 const bf16x8 br = tr2(tile + offR + kk * 2048, 512), bi = tr2(tile + offI + kk * 2048, 512);
;                 aR = __builtin_amdgcn_mfma_f32_32x32x16_bf16(ac, br, aR, 0, 0, 0); aR = __builtin_amdgcn_mfma_f32_32x32x16_bf16(as, bi, aR, 0, 0, 0);
;                 aI = __builtin_amdgcn_mfma_f32_32x32x16_bf16(ac, bi, aI, 0, 0, 0); aI = __builtin_amdgcn_mfma_f32_32x32x16_bf16(negbf(as), br, aI, 0, 0, 0);
;             }
; #pragma unroll
;             for (int i = 0; i < 16; ++i) { const int ka = 32 * mb + 8 * (i >> 2) + 4 * hh + (i & 3); const float tc = TW[ka * 64 + sf], ts = TW[8192 + ka * 64 + sf];
;                 const float r2 = tc * aR[i] + ts * aI[i], i2 = tc * aI[i] - ts * aR[i]; bf16_t* op = YB + (size_t)(b * SEQ + ka * 64 + sf) * 512 + 128 * g + 32 * nh + r32;
;                 op[0] = bf1(r2); op[64] = bf1(i2); }
	v_mfma_f32_32x32x16_bf16 v[4:19], v[136:139], v[200:203], v[4:19]
	v_xor_b32_e32 v68, 0x80008000, v136
	v_xor_b32_e32 v69, 0x80008000, v137
	v_xor_b32_e32 v70, 0x80008000, v138
	v_xor_b32_e32 v71, 0x80008000, v139
	v_mfma_f32_32x32x16_bf16 v[20:35], v[132:135], v[200:203], v[20:35]
	s_nop 0
	v_mfma_f32_32x32x16_bf16 v[20:35], v[68:71], v[196:199], v[20:35]
	v_mfma_f32_32x32x16_bf16 v[4:19], v[140:143], v[204:207], v[4:19]
	v_mfma_f32_32x32x16_bf16 v[4:19], v[60:63], v[64:67], v[4:19]
	v_xor_b32_e32 v68, 0x80008000, v60
	v_xor_b32_e32 v69, 0x80008000, v61
	v_xor_b32_e32 v70, 0x80008000, v62
	v_xor_b32_e32 v71, 0x80008000, v63
	v_mfma_f32_32x32x16_bf16 v[20:35], v[140:143], v[64:67], v[20:35]
	s_nop 0
	v_mfma_f32_32x32x16_bf16 v[20:35], v[68:71], v[204:207], v[20:35]
	global_load_dwordx4 v[84:87], v[38:39], off
	global_load_dwordx4 v[88:91], v[38:39], off offset:256
	global_load_dwordx4 v[92:95], v[38:39], off offset:32
	global_load_dwordx4 v[96:99], v[38:39], off offset:288
	global_load_dwordx4 v[100:103], v[38:39], off offset:64
	global_load_dwordx4 v[104:107], v[38:39], off offset:320
	global_load_dwordx4 v[108:111], v[38:39], off offset:96
	global_load_dwordx4 v[112:115], v[38:39], off offset:352
	global_load_dwordx4 v[116:119], v[38:39], off offset:128
	global_load_dwordx4 v[120:123], v[38:39], off offset:384
	global_load_dwordx4 v[124:127], v[38:39], off offset:160
	global_load_dwordx4 v[128:131], v[38:39], off offset:416
	global_load_dwordx4 v[132:135], v[38:39], off offset:192
	global_load_dwordx4 v[136:139], v[38:39], off offset:448
	global_load_dwordx4 v[140:143], v[38:39], off offset:224
	global_load_dwordx4 v[60:63], v[38:39], off offset:480
	s_waitcnt vmcnt(16)
	s_nop 15
	v_mul_f32_e32 v235, v20, v213
	v_mul_f32_e32 v236, v4, v213
	v_fmac_f32_e32 v235, v4, v42
	v_fma_f32 v236, v20, v42, -v236
	v_cvt_pk_bf16_f32 v235, v235, v235
	v_cvt_pk_bf16_f32 v236, v236, v236
	ds_write_b16 v237, v235 offset:0
	ds_write_b16 v237, v236 offset:64
	v_mul_f32_e32 v235, v21, v214
	v_mul_f32_e32 v236, v5, v214
	v_fmac_f32_e32 v235, v5, v43
	v_fma_f32 v236, v21, v43, -v236
	v_cvt_pk_bf16_f32 v235, v235, v235
	v_cvt_pk_bf16_f32 v236, v236, v236
	ds_write_b16 v237, v235 offset:128
	ds_write_b16 v237, v236 offset:192
	v_mul_f32_e32 v235, v22, v215
	v_mul_f32_e32 v236, v6, v215
	v_fmac_f32_e32 v235, v6, v44
	v_fma_f32 v236, v22, v44, -v236
	v_cvt_pk_bf16_f32 v235, v235, v235
	v_cvt_pk_bf16_f32 v236, v236, v236
	ds_write_b16 v237, v235 offset:256
	ds_write_b16 v237, v236 offset:320
	v_mul_f32_e32 v235, v23, v216
	v_mul_f32_e32 v236, v7, v216
	v_fmac_f32_e32 v235, v7, v45
	v_fma_f32 v236, v23, v45, -v236
	v_cvt_pk_bf16_f32 v235, v235, v235
	v_cvt_pk_bf16_f32 v236, v236, v236
	ds_write_b16 v237, v235 offset:384
	ds_write_b16 v237, v236 offset:448
	v_mul_f32_e32 v235, v24, v217
	v_mul_f32_e32 v236, v8, v217
	v_fmac_f32_e32 v235, v8, v46
	v_fma_f32 v236, v24, v46, -v236
	v_cvt_pk_bf16_f32 v235, v235, v235
	v_cvt_pk_bf16_f32 v236, v236, v236
	ds_write_b16 v237, v235 offset:1024
	ds_write_b16 v237, v236 offset:1088
	v_mul_f32_e32 v235, v25, v218
	v_mul_f32_e32 v236, v9, v218
	v_fmac_f32_e32 v235, v9, v47
	v_fma_f32 v236, v25, v47, -v236
	v_cvt_pk_bf16_f32 v235, v235, v235
	v_cvt_pk_bf16_f32 v236, v236, v236
	ds_write_b16 v237, v235 offset:1152
	ds_write_b16 v237, v236 offset:1216
	v_mul_f32_e32 v235, v26, v219
	v_mul_f32_e32 v236, v10, v219
	v_fmac_f32_e32 v235, v10, v48
	v_fma_f32 v236, v26, v48, -v236
	v_cvt_pk_bf16_f32 v235, v235, v235
	v_cvt_pk_bf16_f32 v236, v236, v236
	ds_write_b16 v237, v235 offset:1280
	ds_write_b16 v237, v236 offset:1344
	v_mul_f32_e32 v235, v27, v220
	v_mul_f32_e32 v236, v11, v220
	v_fmac_f32_e32 v235, v11, v49
	v_fma_f32 v236, v27, v49, -v236
	v_cvt_pk_bf16_f32 v235, v235, v235
	v_cvt_pk_bf16_f32 v236, v236, v236
	ds_write_b16 v237, v235 offset:1408
	ds_write_b16 v237, v236 offset:1472
	v_mul_f32_e32 v235, v28, v221
	v_mul_f32_e32 v236, v12, v221
	v_fmac_f32_e32 v235, v12, v50
	v_fma_f32 v236, v28, v50, -v236
	v_cvt_pk_bf16_f32 v235, v235, v235
	v_cvt_pk_bf16_f32 v236, v236, v236
	ds_write_b16 v237, v235 offset:2048
	ds_write_b16 v237, v236 offset:2112
	v_mul_f32_e32 v235, v29, v222
	v_mul_f32_e32 v236, v13, v222
	v_fmac_f32_e32 v235, v13, v51
	v_fma_f32 v236, v29, v51, -v236
	v_cvt_pk_bf16_f32 v235, v235, v235
	v_cvt_pk_bf16_f32 v236, v236, v236
	ds_write_b16 v237, v235 offset:2176
	ds_write_b16 v237, v236 offset:2240
	v_mul_f32_e32 v235, v30, v223
	v_mul_f32_e32 v236, v14, v223
	v_fmac_f32_e32 v235, v14, v52
	v_fma_f32 v236, v30, v52, -v236
	v_cvt_pk_bf16_f32 v235, v235, v235
	v_cvt_pk_bf16_f32 v236, v236, v236
	ds_write_b16 v237, v235 offset:2304
	ds_write_b16 v237, v236 offset:2368
	v_mul_f32_e32 v235, v31, v224
	v_mul_f32_e32 v236, v15, v224
	v_fmac_f32_e32 v235, v15, v53
	v_fma_f32 v236, v31, v53, -v236
	v_cvt_pk_bf16_f32 v235, v235, v235
	v_cvt_pk_bf16_f32 v236, v236, v236
	ds_write_b16 v237, v235 offset:2432
	ds_write_b16 v237, v236 offset:2496
	v_mul_f32_e32 v235, v32, v225
	v_mul_f32_e32 v236, v16, v225
	v_fmac_f32_e32 v235, v16, v54
	v_fma_f32 v236, v32, v54, -v236
	v_cvt_pk_bf16_f32 v235, v235, v235
	v_cvt_pk_bf16_f32 v236, v236, v236
	ds_write_b16 v237, v235 offset:3072
	ds_write_b16 v237, v236 offset:3136
	v_mul_f32_e32 v235, v33, v226
	v_mul_f32_e32 v236, v17, v226
	v_fmac_f32_e32 v235, v17, v55
	v_fma_f32 v236, v33, v55, -v236
	v_cvt_pk_bf16_f32 v235, v235, v235
	v_cvt_pk_bf16_f32 v236, v236, v236
	ds_write_b16 v237, v235 offset:3200
	ds_write_b16 v237, v236 offset:3264
	v_mul_f32_e32 v235, v34, v227
	v_mul_f32_e32 v236, v18, v227
	v_fmac_f32_e32 v235, v18, v56
	v_fma_f32 v236, v34, v56, -v236
; __device__ __forceinline__ bf16_t bf1(float v) { return (bf16_t)pk2(v, 0.f); }
; __device__ __forceinline__ void dft1_mfma(const bf16_t* U, bf16_t* YB, const bf16_t* A1, const float* TW, LAS unsigned char* tile, int gw, int NGW, int lane) {
;     ...
;             const bf16_t* ap = A1 + (size_t)(32 * mb + r32) * 256 + 8 * hh;
; #pragma unroll
;             for (int kk = 0; kk < 8; ++kk) {
;                 const bf16x8 ac = *(const bf16x8*)(ap + 16 * kk), as = *(const bf16x8*)(ap + 128 + 16 * kk);
;                 const bf16x8 br = tr2(tile + offR + kk * 2048, 512), bi = tr2(tile + offI + kk * 2048, 512);
;                 aR = __builtin_amdgcn_mfma_f32_32x32x16_bf16(ac, br, aR, 0, 0, 0); aR = __builtin_amdgcn_mfma_f32_32x32x16_bf16(as, bi, aR, 0, 0, 0);
;                 aI = __builtin_amdgcn_mfma_f32_32x32x16_bf16(ac, bi, aI, 0, 0, 0); aI = __builtin_amdgcn_mfma_f32_32x32x16_bf16(negbf(as), br, aI, 0, 0, 0);
;             }
; #pragma unroll
;             for (int i = 0; i < 16; ++i) { const int ka = 32 * mb + 8 * (i >> 2) + 4 * hh + (i & 3); const float tc = TW[ka * 64 + sf], ts = TW[8192 + ka * 64 + sf];
;                 const float r2 = tc * aR[i] + ts * aI[i], i2 = tc * aI[i] - ts * aR[i]; bf16_t* op = YB + (size_t)(b * SEQ + ka * 64 + sf) * 512 + 128 * g + 32 * nh + r32;
;                 op[0] = bf1(r2); op[64] = bf1(i2); }
	v_cvt_pk_bf16_f32 v235, v235, v235
	v_cvt_pk_bf16_f32 v236, v236, v236
	ds_write_b16 v237, v235 offset:3328
	ds_write_b16 v237, v236 offset:3392
	v_mul_f32_e32 v235, v35, v228
	v_mul_f32_e32 v236, v19, v228
	v_fmac_f32_e32 v235, v19, v57
	v_fma_f32 v236, v35, v57, -v236
	v_cvt_pk_bf16_f32 v235, v235, v235
	v_cvt_pk_bf16_f32 v236, v236, v236
	ds_write_b16 v237, v235 offset:3456
	ds_write_b16 v237, v236 offset:3520
	v_or_b32_e32 v231, 0x2000, v229
	v_add_u32_e32 v232, 0x8000, v231
	global_load_dword v42, v231, s[4:5]
	global_load_dword v213, v232, s[4:5]
	v_or_b32_e32 v231, 0x2100, v229
	v_add_u32_e32 v232, 0x8000, v231
	global_load_dword v43, v231, s[4:5]
	global_load_dword v214, v232, s[4:5]
	v_or_b32_e32 v231, 0x2200, v229
	v_add_u32_e32 v232, 0x8000, v231
	global_load_dword v44, v231, s[4:5]
	global_load_dword v215, v232, s[4:5]
	v_or_b32_e32 v231, 0x2300, v229
	v_add_u32_e32 v232, 0x8000, v231
	global_load_dword v45, v231, s[4:5]
	global_load_dword v216, v232, s[4:5]
	v_or_b32_e32 v231, 0x2800, v229
	v_add_u32_e32 v232, 0x8000, v231
	global_load_dword v46, v231, s[4:5]
	global_load_dword v217, v232, s[4:5]
	v_or_b32_e32 v231, 0x2900, v229
	v_add_u32_e32 v232, 0x8000, v231
	global_load_dword v47, v231, s[4:5]
	global_load_dword v218, v232, s[4:5]
	v_or_b32_e32 v231, 0x2a00, v229
	v_add_u32_e32 v232, 0x8000, v231
	global_load_dword v48, v231, s[4:5]
	global_load_dword v219, v232, s[4:5]
	v_or_b32_e32 v231, 0x2b00, v229
	v_add_u32_e32 v232, 0x8000, v231
	global_load_dword v49, v231, s[4:5]
	global_load_dword v220, v232, s[4:5]
	v_or_b32_e32 v231, 0x3000, v229
	v_add_u32_e32 v232, 0x8000, v231
	global_load_dword v50, v231, s[4:5]
	global_load_dword v221, v232, s[4:5]
	v_or_b32_e32 v231, 0x3100, v229
	v_add_u32_e32 v232, 0x8000, v231
	global_load_dword v51, v231, s[4:5]
	global_load_dword v222, v232, s[4:5]
	v_or_b32_e32 v231, 0x3200, v229
	v_add_u32_e32 v232, 0x8000, v231
	global_load_dword v52, v231, s[4:5]
	global_load_dword v223, v232, s[4:5]
	v_or_b32_e32 v231, 0x3300, v229
	v_add_u32_e32 v232, 0x8000, v231
	global_load_dword v53, v231, s[4:5]
	global_load_dword v224, v232, s[4:5]
	v_or_b32_e32 v231, 0x3800, v229
	v_add_u32_e32 v232, 0x8000, v231
	global_load_dword v54, v231, s[4:5]
	global_load_dword v225, v232, s[4:5]
	v_or_b32_e32 v231, 0x3900, v229
	v_add_u32_e32 v232, 0x8000, v231
	global_load_dword v55, v231, s[4:5]
	global_load_dword v226, v232, s[4:5]
	v_or_b32_e32 v231, 0x3a00, v229
	v_add_u32_e32 v232, 0x8000, v231
	global_load_dword v56, v231, s[4:5]
	global_load_dword v227, v232, s[4:5]
	v_or_b32_e32 v231, 0x3b00, v229
	v_add_u32_e32 v232, 0x8000, v231
	global_load_dword v57, v231, s[4:5]
	global_load_dword v228, v232, s[4:5]
	s_waitcnt lgkmcnt(0)
	ds_read_b128 v[76:79], v239 offset:0
	ds_read_b128 v[244:247], v239 offset:1024
	ds_read_b128 v[250:253], v239 offset:2048
	ds_read_b128 v[240:243], v239 offset:3072
	s_waitcnt lgkmcnt(3)
	v_add_u32_e32 v234, 0x0, v233
	global_store_dwordx4 v234, v[76:79], s[6:7]
	s_waitcnt lgkmcnt(2)
	v_add_u32_e32 v234, 0x80000, v233
	global_store_dwordx4 v234, v[244:247], s[6:7]
	s_waitcnt lgkmcnt(1)
	v_add_u32_e32 v234, 0x100000, v233
	global_store_dwordx4 v234, v[250:253], s[6:7]
	s_waitcnt lgkmcnt(0)
	v_add_u32_e32 v234, 0x180000, v233
	global_store_dwordx4 v234, v[240:243], s[6:7]
	s_waitcnt vmcnt(36)
	v_mfma_f32_32x32x16_bf16 v[4:19], v[84:87], v[148:151], 0
	v_mfma_f32_32x32x16_bf16 v[4:19], v[88:91], v[152:155], v[4:19]
	v_xor_b32_e32 v68, 0x80008000, v88
	v_xor_b32_e32 v69, 0x80008000, v89
	v_xor_b32_e32 v70, 0x80008000, v90
	v_xor_b32_e32 v71, 0x80008000, v91
	v_mfma_f32_32x32x16_bf16 v[20:35], v[84:87], v[152:155], 0
	s_nop 0
	v_mfma_f32_32x32x16_bf16 v[20:35], v[68:71], v[148:151], v[20:35]
	v_mfma_f32_32x32x16_bf16 v[4:19], v[92:95], v[156:159], v[4:19]
	v_mfma_f32_32x32x16_bf16 v[4:19], v[96:99], v[160:163], v[4:19]
	v_xor_b32_e32 v68, 0x80008000, v96
	v_xor_b32_e32 v69, 0x80008000, v97
	v_xor_b32_e32 v70, 0x80008000, v98
	v_xor_b32_e32 v71, 0x80008000, v99
	v_mfma_f32_32x32x16_bf16 v[20:35], v[92:95], v[160:163], v[20:35]
	s_nop 0
	v_mfma_f32_32x32x16_bf16 v[20:35], v[68:71], v[156:159], v[20:35]
	v_mfma_f32_32x32x16_bf16 v[4:19], v[100:103], v[164:167], v[4:19]
	v_mfma_f32_32x32x16_bf16 v[4:19], v[104:107], v[168:171], v[4:19]
	v_xor_b32_e32 v68, 0x80008000, v104
	v_xor_b32_e32 v69, 0x80008000, v105
	v_xor_b32_e32 v70, 0x80008000, v106
	v_xor_b32_e32 v71, 0x80008000, v107
	v_mfma_f32_32x32x16_bf16 v[20:35], v[100:103], v[168:171], v[20:35]
	s_nop 0
	v_mfma_f32_32x32x16_bf16 v[20:35], v[68:71], v[164:167], v[20:35]
	v_mfma_f32_32x32x16_bf16 v[4:19], v[108:111], v[172:175], v[4:19]
	v_mfma_f32_32x32x16_bf16 v[4:19], v[112:115], v[176:179], v[4:19]
	v_xor_b32_e32 v68, 0x80008000, v112
	v_xor_b32_e32 v69, 0x80008000, v113
	v_xor_b32_e32 v70, 0x80008000, v114
	v_xor_b32_e32 v71, 0x80008000, v115
	v_mfma_f32_32x32x16_bf16 v[20:35], v[108:111], v[176:179], v[20:35]
	s_nop 0
	v_mfma_f32_32x32x16_bf16 v[20:35], v[68:71], v[172:175], v[20:35]
	v_mfma_f32_32x32x16_bf16 v[4:19], v[116:119], v[180:183], v[4:19]
	v_mfma_f32_32x32x16_bf16 v[4:19], v[120:123], v[184:187], v[4:19]
	v_xor_b32_e32 v68, 0x80008000, v120
	v_xor_b32_e32 v69, 0x80008000, v121
	v_xor_b32_e32 v70, 0x80008000, v122
	v_xor_b32_e32 v71, 0x80008000, v123
	v_mfma_f32_32x32x16_bf16 v[20:35], v[116:119], v[184:187], v[20:35]
	s_nop 0
	v_mfma_f32_32x32x16_bf16 v[20:35], v[68:71], v[180:183], v[20:35]
	v_mfma_f32_32x32x16_bf16 v[4:19], v[124:127], v[188:191], v[4:19]
	v_mfma_f32_32x32x16_bf16 v[4:19], v[128:131], v[192:195], v[4:19]
	v_xor_b32_e32 v68, 0x80008000, v128
	v_xor_b32_e32 v69, 0x80008000, v129
; __device__ __forceinline__ bf16_t bf1(float v) { return (bf16_t)pk2(v, 0.f); }
; __device__ __forceinline__ void dft1_mfma(const bf16_t* U, bf16_t* YB, const bf16_t* A1, const float* TW, LAS unsigned char* tile, int gw, int NGW, int lane) {
;     ...
;             const bf16_t* ap = A1 + (size_t)(32 * mb + r32) * 256 + 8 * hh;
; #pragma unroll
;             for (int kk = 0; kk < 8; ++kk) {
;                 const bf16x8 ac = *(const bf16x8*)(ap + 16 * kk), as = *(const bf16x8*)(ap + 128 + 16 * kk);
;                 const bf16x8 br = tr2(tile + offR + kk * 2048, 512), bi = tr2(tile + offI + kk * 2048, 512);
;                 aR = __builtin_amdgcn_mfma_f32_32x32x16_bf16(ac, br, aR, 0, 0, 0); aR = __builtin_amdgcn_mfma_f32_32x32x16_bf16(as, bi, aR, 0, 0, 0);
;                 aI = __builtin_amdgcn_mfma_f32_32x32x16_bf16(ac, bi, aI, 0, 0, 0); aI = __builtin_amdgcn_mfma_f32_32x32x16_bf16(negbf(as), br, aI, 0, 0, 0);
;             }
; #pragma unroll
;             for (int i = 0; i < 16; ++i) { const int ka = 32 * mb + 8 * (i >> 2) + 4 * hh + (i & 3); const float tc = TW[ka * 64 + sf], ts = TW[8192 + ka * 64 + sf];
;                 const float r2 = tc * aR[i] + ts * aI[i], i2 = tc * aI[i] - ts * aR[i]; bf16_t* op = YB + (size_t)(b * SEQ + ka * 64 + sf) * 512 + 128 * g + 32 * nh + r32;
;                 op[0] = bf1(r2); op[64] = bf1(i2); }
	v_xor_b32_e32 v70, 0x80008000, v130
	v_xor_b32_e32 v71, 0x80008000, v131
	v_mfma_f32_32x32x16_bf16 v[20:35], v[124:127], v[192:195], v[20:35]
	s_nop 0
	v_mfma_f32_32x32x16_bf16 v[20:35], v[68:71], v[188:191], v[20:35]
	v_mfma_f32_32x32x16_bf16 v[4:19], v[132:135], v[196:199], v[4:19]
	v_mfma_f32_32x32x16_bf16 v[4:19], v[136:139], v[200:203], v[4:19]
	v_xor_b32_e32 v68, 0x80008000, v136
	v_xor_b32_e32 v69, 0x80008000, v137
	v_xor_b32_e32 v70, 0x80008000, v138
	v_xor_b32_e32 v71, 0x80008000, v139
	v_mfma_f32_32x32x16_bf16 v[20:35], v[132:135], v[200:203], v[20:35]
	s_nop 0
	v_mfma_f32_32x32x16_bf16 v[20:35], v[68:71], v[196:199], v[20:35]
	v_mfma_f32_32x32x16_bf16 v[4:19], v[140:143], v[204:207], v[4:19]
	v_mfma_f32_32x32x16_bf16 v[4:19], v[60:63], v[64:67], v[4:19]
	v_xor_b32_e32 v68, 0x80008000, v60
	v_xor_b32_e32 v69, 0x80008000, v61
	v_xor_b32_e32 v70, 0x80008000, v62
	v_xor_b32_e32 v71, 0x80008000, v63
	v_mfma_f32_32x32x16_bf16 v[20:35], v[140:143], v[64:67], v[20:35]
	s_nop 0
	v_mfma_f32_32x32x16_bf16 v[20:35], v[68:71], v[204:207], v[20:35]
	global_load_dwordx4 v[84:87], v[40:41], off
	global_load_dwordx4 v[88:91], v[40:41], off offset:256
	global_load_dwordx4 v[92:95], v[40:41], off offset:32
	global_load_dwordx4 v[96:99], v[40:41], off offset:288
	global_load_dwordx4 v[100:103], v[40:41], off offset:64
	global_load_dwordx4 v[104:107], v[40:41], off offset:320
	global_load_dwordx4 v[108:111], v[40:41], off offset:96
	global_load_dwordx4 v[112:115], v[40:41], off offset:352
	global_load_dwordx4 v[116:119], v[40:41], off offset:128
	global_load_dwordx4 v[120:123], v[40:41], off offset:384
	global_load_dwordx4 v[124:127], v[40:41], off offset:160
	global_load_dwordx4 v[128:131], v[40:41], off offset:416
	global_load_dwordx4 v[132:135], v[40:41], off offset:192
	global_load_dwordx4 v[136:139], v[40:41], off offset:448
	global_load_dwordx4 v[140:143], v[40:41], off offset:224
	global_load_dwordx4 v[60:63], v[40:41], off offset:480
	s_waitcnt vmcnt(16)
	s_nop 15
	v_mul_f32_e32 v235, v20, v213
	v_mul_f32_e32 v236, v4, v213
	v_fmac_f32_e32 v235, v4, v42
	v_fma_f32 v236, v20, v42, -v236
	v_cvt_pk_bf16_f32 v235, v235, v235
	v_cvt_pk_bf16_f32 v236, v236, v236
	ds_write_b16 v237, v235 offset:4096
	ds_write_b16 v237, v236 offset:4160
	v_mul_f32_e32 v235, v21, v214
	v_mul_f32_e32 v236, v5, v214
	v_fmac_f32_e32 v235, v5, v43
	v_fma_f32 v236, v21, v43, -v236
	v_cvt_pk_bf16_f32 v235, v235, v235
	v_cvt_pk_bf16_f32 v236, v236, v236
	ds_write_b16 v237, v235 offset:4224
	ds_write_b16 v237, v236 offset:4288
	v_mul_f32_e32 v235, v22, v215
	v_mul_f32_e32 v236, v6, v215
	v_fmac_f32_e32 v235, v6, v44
	v_fma_f32 v236, v22, v44, -v236
	v_cvt_pk_bf16_f32 v235, v235, v235
	v_cvt_pk_bf16_f32 v236, v236, v236
	ds_write_b16 v237, v235 offset:4352
	ds_write_b16 v237, v236 offset:4416
	v_mul_f32_e32 v235, v23, v216
	v_mul_f32_e32 v236, v7, v216
	v_fmac_f32_e32 v235, v7, v45
	v_fma_f32 v236, v23, v45, -v236
	v_cvt_pk_bf16_f32 v235, v235, v235
	v_cvt_pk_bf16_f32 v236, v236, v236
	ds_write_b16 v237, v235 offset:4480
	ds_write_b16 v237, v236 offset:4544
	v_mul_f32_e32 v235, v24, v217
	v_mul_f32_e32 v236, v8, v217
	v_fmac_f32_e32 v235, v8, v46
	v_fma_f32 v236, v24, v46, -v236
	v_cvt_pk_bf16_f32 v235, v235, v235
	v_cvt_pk_bf16_f32 v236, v236, v236
	ds_write_b16 v237, v235 offset:5120
	ds_write_b16 v237, v236 offset:5184
	v_mul_f32_e32 v235, v25, v218
	v_mul_f32_e32 v236, v9, v218
	v_fmac_f32_e32 v235, v9, v47
	v_fma_f32 v236, v25, v47, -v236
	v_cvt_pk_bf16_f32 v235, v235, v235
	v_cvt_pk_bf16_f32 v236, v236, v236
	ds_write_b16 v237, v235 offset:5248
	ds_write_b16 v237, v236 offset:5312
	v_mul_f32_e32 v235, v26, v219
	v_mul_f32_e32 v236, v10, v219
	v_fmac_f32_e32 v235, v10, v48
	v_fma_f32 v236, v26, v48, -v236
	v_cvt_pk_bf16_f32 v235, v235, v235
	v_cvt_pk_bf16_f32 v236, v236, v236
	ds_write_b16 v237, v235 offset:5376
	ds_write_b16 v237, v236 offset:5440
	v_mul_f32_e32 v235, v27, v220
	v_mul_f32_e32 v236, v11, v220
	v_fmac_f32_e32 v235, v11, v49
	v_fma_f32 v236, v27, v49, -v236
	v_cvt_pk_bf16_f32 v235, v235, v235
	v_cvt_pk_bf16_f32 v236, v236, v236
	ds_write_b16 v237, v235 offset:5504
	ds_write_b16 v237, v236 offset:5568
	v_mul_f32_e32 v235, v28, v221
	v_mul_f32_e32 v236, v12, v221
	v_fmac_f32_e32 v235, v12, v50
	v_fma_f32 v236, v28, v50, -v236
	v_cvt_pk_bf16_f32 v235, v235, v235
	v_cvt_pk_bf16_f32 v236, v236, v236
	ds_write_b16 v237, v235 offset:6144
	ds_write_b16 v237, v236 offset:6208
	v_mul_f32_e32 v235, v29, v222
	v_mul_f32_e32 v236, v13, v222
	v_fmac_f32_e32 v235, v13, v51
	v_fma_f32 v236, v29, v51, -v236
	v_cvt_pk_bf16_f32 v235, v235, v235
	v_cvt_pk_bf16_f32 v236, v236, v236
	ds_write_b16 v237, v235 offset:6272
	ds_write_b16 v237, v236 offset:6336
	v_mul_f32_e32 v235, v30, v223
	v_mul_f32_e32 v236, v14, v223
	v_fmac_f32_e32 v235, v14, v52
	v_fma_f32 v236, v30, v52, -v236
	v_cvt_pk_bf16_f32 v235, v235, v235
	v_cvt_pk_bf16_f32 v236, v236, v236
	ds_write_b16 v237, v235 offset:6400
	ds_write_b16 v237, v236 offset:6464
	v_mul_f32_e32 v235, v31, v224
	v_mul_f32_e32 v236, v15, v224
	v_fmac_f32_e32 v235, v15, v53
	v_fma_f32 v236, v31, v53, -v236
	v_cvt_pk_bf16_f32 v235, v235, v235
	v_cvt_pk_bf16_f32 v236, v236, v236
	ds_write_b16 v237, v235 offset:6528
	ds_write_b16 v237, v236 offset:6592
	v_mul_f32_e32 v235, v32, v225
	v_mul_f32_e32 v236, v16, v225
	v_fmac_f32_e32 v235, v16, v54
	v_fma_f32 v236, v32, v54, -v236
	v_cvt_pk_bf16_f32 v235, v235, v235
	v_cvt_pk_bf16_f32 v236, v236, v236
	ds_write_b16 v237, v235 offset:7168
	ds_write_b16 v237, v236 offset:7232
	v_mul_f32_e32 v235, v33, v226
	v_mul_f32_e32 v236, v17, v226
	v_fmac_f32_e32 v235, v17, v55
	v_fma_f32 v236, v33, v55, -v236
; __device__ __forceinline__ bf16_t bf1(float v) { return (bf16_t)pk2(v, 0.f); }
; __device__ __forceinline__ void dft1_mfma(const bf16_t* U, bf16_t* YB, const bf16_t* A1, const float* TW, LAS unsigned char* tile, int gw, int NGW, int lane) {
;     ...
;             const bf16_t* ap = A1 + (size_t)(32 * mb + r32) * 256 + 8 * hh;
; #pragma unroll
;             for (int kk = 0; kk < 8; ++kk) {
;                 const bf16x8 ac = *(const bf16x8*)(ap + 16 * kk), as = *(const bf16x8*)(ap + 128 + 16 * kk);
;                 const bf16x8 br = tr2(tile + offR + kk * 2048, 512), bi = tr2(tile + offI + kk * 2048, 512);
;                 aR = __builtin_amdgcn_mfma_f32_32x32x16_bf16(ac, br, aR, 0, 0, 0); aR = __builtin_amdgcn_mfma_f32_32x32x16_bf16(as, bi, aR, 0, 0, 0);
;                 aI = __builtin_amdgcn_mfma_f32_32x32x16_bf16(ac, bi, aI, 0, 0, 0); aI = __builtin_amdgcn_mfma_f32_32x32x16_bf16(negbf(as), br, aI, 0, 0, 0);
;             }
; #pragma unroll
;             for (int i = 0; i < 16; ++i) { const int ka = 32 * mb + 8 * (i >> 2) + 4 * hh + (i & 3); const float tc = TW[ka * 64 + sf], ts = TW[8192 + ka * 64 + sf];
;                 const float r2 = tc * aR[i] + ts * aI[i], i2 = tc * aI[i] - ts * aR[i]; bf16_t* op = YB + (size_t)(b * SEQ + ka * 64 + sf) * 512 + 128 * g + 32 * nh + r32;
;                 op[0] = bf1(r2); op[64] = bf1(i2); }
	v_cvt_pk_bf16_f32 v235, v235, v235
	v_cvt_pk_bf16_f32 v236, v236, v236
	ds_write_b16 v237, v235 offset:7296
	ds_write_b16 v237, v236 offset:7360
	v_mul_f32_e32 v235, v34, v227
	v_mul_f32_e32 v236, v18, v227
	v_fmac_f32_e32 v235, v18, v56
	v_fma_f32 v236, v34, v56, -v236
	v_cvt_pk_bf16_f32 v235, v235, v235
	v_cvt_pk_bf16_f32 v236, v236, v236
	ds_write_b16 v237, v235 offset:7424
	ds_write_b16 v237, v236 offset:7488
	v_mul_f32_e32 v235, v35, v228
	v_mul_f32_e32 v236, v19, v228
	v_fmac_f32_e32 v235, v19, v57
	v_fma_f32 v236, v35, v57, -v236
	v_cvt_pk_bf16_f32 v235, v235, v235
	v_cvt_pk_bf16_f32 v236, v236, v236
	ds_write_b16 v237, v235 offset:7552
	ds_write_b16 v237, v236 offset:7616
	v_or_b32_e32 v231, 0x4000, v229
	v_add_u32_e32 v232, 0x8000, v231
	global_load_dword v42, v231, s[4:5]
	global_load_dword v213, v232, s[4:5]
	v_or_b32_e32 v231, 0x4100, v229
	v_add_u32_e32 v232, 0x8000, v231
	global_load_dword v43, v231, s[4:5]
	global_load_dword v214, v232, s[4:5]
	v_or_b32_e32 v231, 0x4200, v229
	v_add_u32_e32 v232, 0x8000, v231
	global_load_dword v44, v231, s[4:5]
	global_load_dword v215, v232, s[4:5]
	v_or_b32_e32 v231, 0x4300, v229
	v_add_u32_e32 v232, 0x8000, v231
	global_load_dword v45, v231, s[4:5]
	global_load_dword v216, v232, s[4:5]
	v_or_b32_e32 v231, 0x4800, v229
	v_add_u32_e32 v232, 0x8000, v231
	global_load_dword v46, v231, s[4:5]
	global_load_dword v217, v232, s[4:5]
	v_or_b32_e32 v231, 0x4900, v229
	v_add_u32_e32 v232, 0x8000, v231
	global_load_dword v47, v231, s[4:5]
	global_load_dword v218, v232, s[4:5]
	v_or_b32_e32 v231, 0x4a00, v229
	v_add_u32_e32 v232, 0x8000, v231
	global_load_dword v48, v231, s[4:5]
	global_load_dword v219, v232, s[4:5]
	v_or_b32_e32 v231, 0x4b00, v229
	v_add_u32_e32 v232, 0x8000, v231
	global_load_dword v49, v231, s[4:5]
	global_load_dword v220, v232, s[4:5]
	v_or_b32_e32 v231, 0x5000, v229
	v_add_u32_e32 v232, 0x8000, v231
	global_load_dword v50, v231, s[4:5]
	global_load_dword v221, v232, s[4:5]
	v_or_b32_e32 v231, 0x5100, v229
	v_add_u32_e32 v232, 0x8000, v231
	global_load_dword v51, v231, s[4:5]
	global_load_dword v222, v232, s[4:5]
	v_or_b32_e32 v231, 0x5200, v229
	v_add_u32_e32 v232, 0x8000, v231
	global_load_dword v52, v231, s[4:5]
	global_load_dword v223, v232, s[4:5]
	v_or_b32_e32 v231, 0x5300, v229
	v_add_u32_e32 v232, 0x8000, v231
	global_load_dword v53, v231, s[4:5]
	global_load_dword v224, v232, s[4:5]
	v_or_b32_e32 v231, 0x5800, v229
	v_add_u32_e32 v232, 0x8000, v231
	global_load_dword v54, v231, s[4:5]
	global_load_dword v225, v232, s[4:5]
	v_or_b32_e32 v231, 0x5900, v229
	v_add_u32_e32 v232, 0x8000, v231
	global_load_dword v55, v231, s[4:5]
	global_load_dword v226, v232, s[4:5]
	v_or_b32_e32 v231, 0x5a00, v229
	v_add_u32_e32 v232, 0x8000, v231
	global_load_dword v56, v231, s[4:5]
	global_load_dword v227, v232, s[4:5]
	v_or_b32_e32 v231, 0x5b00, v229
	v_add_u32_e32 v232, 0x8000, v231
	global_load_dword v57, v231, s[4:5]
	global_load_dword v228, v232, s[4:5]
	s_waitcnt lgkmcnt(0)
	ds_read_b128 v[76:79], v239 offset:4096
	ds_read_b128 v[244:247], v239 offset:5120
	ds_read_b128 v[250:253], v239 offset:6144
	ds_read_b128 v[240:243], v239 offset:7168
	s_waitcnt lgkmcnt(3)
	v_add_u32_e32 v234, 0x200000, v233
	global_store_dwordx4 v234, v[76:79], s[6:7]
	s_waitcnt lgkmcnt(2)
	v_add_u32_e32 v234, 0x280000, v233
	global_store_dwordx4 v234, v[244:247], s[6:7]
	s_waitcnt lgkmcnt(1)
	v_add_u32_e32 v234, 0x300000, v233
	global_store_dwordx4 v234, v[250:253], s[6:7]
	s_waitcnt lgkmcnt(0)
	v_add_u32_e32 v234, 0x380000, v233
	global_store_dwordx4 v234, v[240:243], s[6:7]
	s_waitcnt vmcnt(36)
	v_mfma_f32_32x32x16_bf16 v[4:19], v[84:87], v[148:151], 0
	v_mfma_f32_32x32x16_bf16 v[4:19], v[88:91], v[152:155], v[4:19]
	v_xor_b32_e32 v68, 0x80008000, v88
	v_xor_b32_e32 v69, 0x80008000, v89
	v_xor_b32_e32 v70, 0x80008000, v90
	v_xor_b32_e32 v71, 0x80008000, v91
	v_mfma_f32_32x32x16_bf16 v[20:35], v[84:87], v[152:155], 0
	s_nop 0
	v_mfma_f32_32x32x16_bf16 v[20:35], v[68:71], v[148:151], v[20:35]
	v_mfma_f32_32x32x16_bf16 v[4:19], v[92:95], v[156:159], v[4:19]
	v_mfma_f32_32x32x16_bf16 v[4:19], v[96:99], v[160:163], v[4:19]
	v_xor_b32_e32 v68, 0x80008000, v96
	v_xor_b32_e32 v69, 0x80008000, v97
	v_xor_b32_e32 v70, 0x80008000, v98
	v_xor_b32_e32 v71, 0x80008000, v99
	v_mfma_f32_32x32x16_bf16 v[20:35], v[92:95], v[160:163], v[20:35]
	s_nop 0
	v_mfma_f32_32x32x16_bf16 v[20:35], v[68:71], v[156:159], v[20:35]
	v_mfma_f32_32x32x16_bf16 v[4:19], v[100:103], v[164:167], v[4:19]
	v_mfma_f32_32x32x16_bf16 v[4:19], v[104:107], v[168:171], v[4:19]
	v_xor_b32_e32 v68, 0x80008000, v104
	v_xor_b32_e32 v69, 0x80008000, v105
	v_xor_b32_e32 v70, 0x80008000, v106
	v_xor_b32_e32 v71, 0x80008000, v107
	v_mfma_f32_32x32x16_bf16 v[20:35], v[100:103], v[168:171], v[20:35]
	s_nop 0
	v_mfma_f32_32x32x16_bf16 v[20:35], v[68:71], v[164:167], v[20:35]
	v_mfma_f32_32x32x16_bf16 v[4:19], v[108:111], v[172:175], v[4:19]
	v_mfma_f32_32x32x16_bf16 v[4:19], v[112:115], v[176:179], v[4:19]
	v_xor_b32_e32 v68, 0x80008000, v112
	v_xor_b32_e32 v69, 0x80008000, v113
	v_xor_b32_e32 v70, 0x80008000, v114
	v_xor_b32_e32 v71, 0x80008000, v115
	v_mfma_f32_32x32x16_bf16 v[20:35], v[108:111], v[176:179], v[20:35]
	s_nop 0
	v_mfma_f32_32x32x16_bf16 v[20:35], v[68:71], v[172:175], v[20:35]
	v_mfma_f32_32x32x16_bf16 v[4:19], v[116:119], v[180:183], v[4:19]
	v_mfma_f32_32x32x16_bf16 v[4:19], v[120:123], v[184:187], v[4:19]
	v_xor_b32_e32 v68, 0x80008000, v120
	v_xor_b32_e32 v69, 0x80008000, v121
	v_xor_b32_e32 v70, 0x80008000, v122
	v_xor_b32_e32 v71, 0x80008000, v123
	v_mfma_f32_32x32x16_bf16 v[20:35], v[116:119], v[184:187], v[20:35]
	s_nop 0
; __device__ __forceinline__ bf16_t bf1(float v) { return (bf16_t)pk2(v, 0.f); }
; __device__ __forceinline__ void dft1_mfma(const bf16_t* U, bf16_t* YB, const bf16_t* A1, const float* TW, LAS unsigned char* tile, int gw, int NGW, int lane) {
;     ...
;             const bf16_t* ap = A1 + (size_t)(32 * mb + r32) * 256 + 8 * hh;
; #pragma unroll
;             for (int kk = 0; kk < 8; ++kk) {
;                 const bf16x8 ac = *(const bf16x8*)(ap + 16 * kk), as = *(const bf16x8*)(ap + 128 + 16 * kk);
;                 const bf16x8 br = tr2(tile + offR + kk * 2048, 512), bi = tr2(tile + offI + kk * 2048, 512);
;                 aR = __builtin_amdgcn_mfma_f32_32x32x16_bf16(ac, br, aR, 0, 0, 0); aR = __builtin_amdgcn_mfma_f32_32x32x16_bf16(as, bi, aR, 0, 0, 0);
;                 aI = __builtin_amdgcn_mfma_f32_32x32x16_bf16(ac, bi, aI, 0, 0, 0); aI = __builtin_amdgcn_mfma_f32_32x32x16_bf16(negbf(as), br, aI, 0, 0, 0);
;             }
; #pragma unroll
;             for (int i = 0; i < 16; ++i) { const int ka = 32 * mb + 8 * (i >> 2) + 4 * hh + (i & 3); const float tc = TW[ka * 64 + sf], ts = TW[8192 + ka * 64 + sf];
;                 const float r2 = tc * aR[i] + ts * aI[i], i2 = tc * aI[i] - ts * aR[i]; bf16_t* op = YB + (size_t)(b * SEQ + ka * 64 + sf) * 512 + 128 * g + 32 * nh + r32;
;                 op[0] = bf1(r2); op[64] = bf1(i2); }
	v_mfma_f32_32x32x16_bf16 v[20:35], v[68:71], v[180:183], v[20:35]
	v_mfma_f32_32x32x16_bf16 v[4:19], v[124:127], v[188:191], v[4:19]
	v_mfma_f32_32x32x16_bf16 v[4:19], v[128:131], v[192:195], v[4:19]
	v_xor_b32_e32 v68, 0x80008000, v128
	v_xor_b32_e32 v69, 0x80008000, v129
	v_xor_b32_e32 v70, 0x80008000, v130
	v_xor_b32_e32 v71, 0x80008000, v131
	v_mfma_f32_32x32x16_bf16 v[20:35], v[124:127], v[192:195], v[20:35]
	s_nop 0
	v_mfma_f32_32x32x16_bf16 v[20:35], v[68:71], v[188:191], v[20:35]
	v_mfma_f32_32x32x16_bf16 v[4:19], v[132:135], v[196:199], v[4:19]
	v_mfma_f32_32x32x16_bf16 v[4:19], v[136:139], v[200:203], v[4:19]
	v_xor_b32_e32 v68, 0x80008000, v136
	v_xor_b32_e32 v69, 0x80008000, v137
	v_xor_b32_e32 v70, 0x80008000, v138
	v_xor_b32_e32 v71, 0x80008000, v139
	v_mfma_f32_32x32x16_bf16 v[20:35], v[132:135], v[200:203], v[20:35]
	s_nop 0
	v_mfma_f32_32x32x16_bf16 v[20:35], v[68:71], v[196:199], v[20:35]
	v_mfma_f32_32x32x16_bf16 v[4:19], v[140:143], v[204:207], v[4:19]
	v_mfma_f32_32x32x16_bf16 v[4:19], v[60:63], v[64:67], v[4:19]
	v_xor_b32_e32 v68, 0x80008000, v60
	v_xor_b32_e32 v69, 0x80008000, v61
	v_xor_b32_e32 v70, 0x80008000, v62
	v_xor_b32_e32 v71, 0x80008000, v63
	v_mfma_f32_32x32x16_bf16 v[20:35], v[140:143], v[64:67], v[20:35]
	s_nop 0
	v_mfma_f32_32x32x16_bf16 v[20:35], v[68:71], v[204:207], v[20:35]
	global_load_dwordx4 v[84:87], v[72:73], off
	global_load_dwordx4 v[88:91], v[72:73], off offset:256
	global_load_dwordx4 v[92:95], v[72:73], off offset:32
	global_load_dwordx4 v[96:99], v[72:73], off offset:288
	global_load_dwordx4 v[100:103], v[72:73], off offset:64
	global_load_dwordx4 v[104:107], v[72:73], off offset:320
	global_load_dwordx4 v[108:111], v[72:73], off offset:96
	global_load_dwordx4 v[112:115], v[72:73], off offset:352
	global_load_dwordx4 v[116:119], v[72:73], off offset:128
	global_load_dwordx4 v[120:123], v[72:73], off offset:384
	global_load_dwordx4 v[124:127], v[72:73], off offset:160
	global_load_dwordx4 v[128:131], v[72:73], off offset:416
	global_load_dwordx4 v[132:135], v[72:73], off offset:192
	global_load_dwordx4 v[136:139], v[72:73], off offset:448
	global_load_dwordx4 v[140:143], v[72:73], off offset:224
	global_load_dwordx4 v[60:63], v[72:73], off offset:480
	s_waitcnt vmcnt(16)
	s_nop 15
	v_mul_f32_e32 v235, v20, v213
	v_mul_f32_e32 v236, v4, v213
	v_fmac_f32_e32 v235, v4, v42
	v_fma_f32 v236, v20, v42, -v236
	v_cvt_pk_bf16_f32 v235, v235, v235
	v_cvt_pk_bf16_f32 v236, v236, v236
	ds_write_b16 v237, v235 offset:8192
	ds_write_b16 v237, v236 offset:8256
	v_mul_f32_e32 v235, v21, v214
	v_mul_f32_e32 v236, v5, v214
	v_fmac_f32_e32 v235, v5, v43
	v_fma_f32 v236, v21, v43, -v236
	v_cvt_pk_bf16_f32 v235, v235, v235
	v_cvt_pk_bf16_f32 v236, v236, v236
	ds_write_b16 v237, v235 offset:8320
	ds_write_b16 v237, v236 offset:8384
	v_mul_f32_e32 v235, v22, v215
	v_mul_f32_e32 v236, v6, v215
	v_fmac_f32_e32 v235, v6, v44
	v_fma_f32 v236, v22, v44, -v236
	v_cvt_pk_bf16_f32 v235, v235, v235
	v_cvt_pk_bf16_f32 v236, v236, v236
	ds_write_b16 v237, v235 offset:8448
	ds_write_b16 v237, v236 offset:8512
	v_mul_f32_e32 v235, v23, v216
	v_mul_f32_e32 v236, v7, v216
	v_fmac_f32_e32 v235, v7, v45
	v_fma_f32 v236, v23, v45, -v236
	v_cvt_pk_bf16_f32 v235, v235, v235
	v_cvt_pk_bf16_f32 v236, v236, v236
	ds_write_b16 v237, v235 offset:8576
	ds_write_b16 v237, v236 offset:8640
	v_mul_f32_e32 v235, v24, v217
	v_mul_f32_e32 v236, v8, v217
	v_fmac_f32_e32 v235, v8, v46
	v_fma_f32 v236, v24, v46, -v236
	v_cvt_pk_bf16_f32 v235, v235, v235
	v_cvt_pk_bf16_f32 v236, v236, v236
	ds_write_b16 v237, v235 offset:9216
	ds_write_b16 v237, v236 offset:9280
	v_mul_f32_e32 v235, v25, v218
	v_mul_f32_e32 v236, v9, v218
	v_fmac_f32_e32 v235, v9, v47
	v_fma_f32 v236, v25, v47, -v236
	v_cvt_pk_bf16_f32 v235, v235, v235
	v_cvt_pk_bf16_f32 v236, v236, v236
	ds_write_b16 v237, v235 offset:9344
	ds_write_b16 v237, v236 offset:9408
	v_mul_f32_e32 v235, v26, v219
	v_mul_f32_e32 v236, v10, v219
	v_fmac_f32_e32 v235, v10, v48
	v_fma_f32 v236, v26, v48, -v236
	v_cvt_pk_bf16_f32 v235, v235, v235
	v_cvt_pk_bf16_f32 v236, v236, v236
	ds_write_b16 v237, v235 offset:9472
	ds_write_b16 v237, v236 offset:9536
	v_mul_f32_e32 v235, v27, v220
	v_mul_f32_e32 v236, v11, v220
	v_fmac_f32_e32 v235, v11, v49
	v_fma_f32 v236, v27, v49, -v236
	v_cvt_pk_bf16_f32 v235, v235, v235
	v_cvt_pk_bf16_f32 v236, v236, v236
	ds_write_b16 v237, v235 offset:9600
	ds_write_b16 v237, v236 offset:9664
	v_mul_f32_e32 v235, v28, v221
	v_mul_f32_e32 v236, v12, v221
	v_fmac_f32_e32 v235, v12, v50
	v_fma_f32 v236, v28, v50, -v236
	v_cvt_pk_bf16_f32 v235, v235, v235
	v_cvt_pk_bf16_f32 v236, v236, v236
	ds_write_b16 v237, v235 offset:10240
	ds_write_b16 v237, v236 offset:10304
	v_mul_f32_e32 v235, v29, v222
	v_mul_f32_e32 v236, v13, v222
	v_fmac_f32_e32 v235, v13, v51
	v_fma_f32 v236, v29, v51, -v236
	v_cvt_pk_bf16_f32 v235, v235, v235
	v_cvt_pk_bf16_f32 v236, v236, v236
	ds_write_b16 v237, v235 offset:10368
	ds_write_b16 v237, v236 offset:10432
	v_mul_f32_e32 v235, v30, v223
	v_mul_f32_e32 v236, v14, v223
	v_fmac_f32_e32 v235, v14, v52
	v_fma_f32 v236, v30, v52, -v236
	v_cvt_pk_bf16_f32 v235, v235, v235
	v_cvt_pk_bf16_f32 v236, v236, v236
	ds_write_b16 v237, v235 offset:10496
	ds_write_b16 v237, v236 offset:10560
	v_mul_f32_e32 v235, v31, v224
	v_mul_f32_e32 v236, v15, v224
	v_fmac_f32_e32 v235, v15, v53
	v_fma_f32 v236, v31, v53, -v236
	v_cvt_pk_bf16_f32 v235, v235, v235
	v_cvt_pk_bf16_f32 v236, v236, v236
	ds_write_b16 v237, v235 offset:10624
	ds_write_b16 v237, v236 offset:10688
	v_mul_f32_e32 v235, v32, v225
	v_mul_f32_e32 v236, v16, v225
	v_fmac_f32_e32 v235, v16, v54
; __device__ __forceinline__ bf16_t bf1(float v) { return (bf16_t)pk2(v, 0.f); }
; __device__ __forceinline__ void dft1_mfma(const bf16_t* U, bf16_t* YB, const bf16_t* A1, const float* TW, LAS unsigned char* tile, int gw, int NGW, int lane) {
;     ...
;             const bf16_t* ap = A1 + (size_t)(32 * mb + r32) * 256 + 8 * hh;
; #pragma unroll
;             for (int kk = 0; kk < 8; ++kk) {
;                 const bf16x8 ac = *(const bf16x8*)(ap + 16 * kk), as = *(const bf16x8*)(ap + 128 + 16 * kk);
;                 const bf16x8 br = tr2(tile + offR + kk * 2048, 512), bi = tr2(tile + offI + kk * 2048, 512);
;                 aR = __builtin_amdgcn_mfma_f32_32x32x16_bf16(ac, br, aR, 0, 0, 0); aR = __builtin_amdgcn_mfma_f32_32x32x16_bf16(as, bi, aR, 0, 0, 0);
;                 aI = __builtin_amdgcn_mfma_f32_32x32x16_bf16(ac, bi, aI, 0, 0, 0); aI = __builtin_amdgcn_mfma_f32_32x32x16_bf16(negbf(as), br, aI, 0, 0, 0);
;             }
; #pragma unroll
;             for (int i = 0; i < 16; ++i) { const int ka = 32 * mb + 8 * (i >> 2) + 4 * hh + (i & 3); const float tc = TW[ka * 64 + sf], ts = TW[8192 + ka * 64 + sf];
;                 const float r2 = tc * aR[i] + ts * aI[i], i2 = tc * aI[i] - ts * aR[i]; bf16_t* op = YB + (size_t)(b * SEQ + ka * 64 + sf) * 512 + 128 * g + 32 * nh + r32;
;                 op[0] = bf1(r2); op[64] = bf1(i2); }
	v_fma_f32 v236, v32, v54, -v236
	v_cvt_pk_bf16_f32 v235, v235, v235
	v_cvt_pk_bf16_f32 v236, v236, v236
	ds_write_b16 v237, v235 offset:11264
	ds_write_b16 v237, v236 offset:11328
	v_mul_f32_e32 v235, v33, v226
	v_mul_f32_e32 v236, v17, v226
	v_fmac_f32_e32 v235, v17, v55
	v_fma_f32 v236, v33, v55, -v236
	v_cvt_pk_bf16_f32 v235, v235, v235
	v_cvt_pk_bf16_f32 v236, v236, v236
	ds_write_b16 v237, v235 offset:11392
	ds_write_b16 v237, v236 offset:11456
	v_mul_f32_e32 v235, v34, v227
	v_mul_f32_e32 v236, v18, v227
	v_fmac_f32_e32 v235, v18, v56
	v_fma_f32 v236, v34, v56, -v236
	v_cvt_pk_bf16_f32 v235, v235, v235
	v_cvt_pk_bf16_f32 v236, v236, v236
	ds_write_b16 v237, v235 offset:11520
	ds_write_b16 v237, v236 offset:11584
	v_mul_f32_e32 v235, v35, v228
	v_mul_f32_e32 v236, v19, v228
	v_fmac_f32_e32 v235, v19, v57
	v_fma_f32 v236, v35, v57, -v236
	v_cvt_pk_bf16_f32 v235, v235, v235
	v_cvt_pk_bf16_f32 v236, v236, v236
	ds_write_b16 v237, v235 offset:11648
	ds_write_b16 v237, v236 offset:11712
	v_or_b32_e32 v231, 0x6000, v229
	v_add_u32_e32 v232, 0x8000, v231
	global_load_dword v42, v231, s[4:5]
	global_load_dword v213, v232, s[4:5]
	v_or_b32_e32 v231, 0x6100, v229
	v_add_u32_e32 v232, 0x8000, v231
	global_load_dword v43, v231, s[4:5]
	global_load_dword v214, v232, s[4:5]
	v_or_b32_e32 v231, 0x6200, v229
	v_add_u32_e32 v232, 0x8000, v231
	global_load_dword v44, v231, s[4:5]
	global_load_dword v215, v232, s[4:5]
	v_or_b32_e32 v231, 0x6300, v229
	v_add_u32_e32 v232, 0x8000, v231
	global_load_dword v45, v231, s[4:5]
	global_load_dword v216, v232, s[4:5]
	v_or_b32_e32 v231, 0x6800, v229
	v_add_u32_e32 v232, 0x8000, v231
	global_load_dword v46, v231, s[4:5]
	global_load_dword v217, v232, s[4:5]
	v_or_b32_e32 v231, 0x6900, v229
	v_add_u32_e32 v232, 0x8000, v231
	global_load_dword v47, v231, s[4:5]
	global_load_dword v218, v232, s[4:5]
	v_or_b32_e32 v231, 0x6a00, v229
	v_add_u32_e32 v232, 0x8000, v231
	global_load_dword v48, v231, s[4:5]
	global_load_dword v219, v232, s[4:5]
	v_or_b32_e32 v231, 0x6b00, v229
	v_add_u32_e32 v232, 0x8000, v231
	global_load_dword v49, v231, s[4:5]
	global_load_dword v220, v232, s[4:5]
	v_or_b32_e32 v231, 0x7000, v229
	v_add_u32_e32 v232, 0x8000, v231
	global_load_dword v50, v231, s[4:5]
	global_load_dword v221, v232, s[4:5]
	v_or_b32_e32 v231, 0x7100, v229
	v_add_u32_e32 v232, 0x8000, v231
	global_load_dword v51, v231, s[4:5]
	global_load_dword v222, v232, s[4:5]
	v_or_b32_e32 v231, 0x7200, v229
	v_add_u32_e32 v232, 0x8000, v231
	global_load_dword v52, v231, s[4:5]
	global_load_dword v223, v232, s[4:5]
	v_or_b32_e32 v231, 0x7300, v229
	v_add_u32_e32 v232, 0x8000, v231
	global_load_dword v53, v231, s[4:5]
	global_load_dword v224, v232, s[4:5]
	v_or_b32_e32 v231, 0x7800, v229
	v_add_u32_e32 v232, 0x8000, v231
	global_load_dword v54, v231, s[4:5]
	global_load_dword v225, v232, s[4:5]
	v_or_b32_e32 v231, 0x7900, v229
	v_add_u32_e32 v232, 0x8000, v231
	global_load_dword v55, v231, s[4:5]
	global_load_dword v226, v232, s[4:5]
	v_or_b32_e32 v231, 0x7a00, v229
	v_add_u32_e32 v232, 0x8000, v231
	global_load_dword v56, v231, s[4:5]
	global_load_dword v227, v232, s[4:5]
	v_or_b32_e32 v231, 0x7b00, v229
	v_add_u32_e32 v232, 0x8000, v231
	global_load_dword v57, v231, s[4:5]
	global_load_dword v228, v232, s[4:5]
	s_waitcnt lgkmcnt(0)
	ds_read_b128 v[76:79], v239 offset:8192
	ds_read_b128 v[244:247], v239 offset:9216
	ds_read_b128 v[250:253], v239 offset:10240
	ds_read_b128 v[240:243], v239 offset:11264
	s_waitcnt lgkmcnt(3)
	v_add_u32_e32 v234, 0x400000, v233
	global_store_dwordx4 v234, v[76:79], s[6:7]
	s_waitcnt lgkmcnt(2)
	v_add_u32_e32 v234, 0x480000, v233
	global_store_dwordx4 v234, v[244:247], s[6:7]
	s_waitcnt lgkmcnt(1)
	v_add_u32_e32 v234, 0x500000, v233
	global_store_dwordx4 v234, v[250:253], s[6:7]
	s_waitcnt lgkmcnt(0)
	v_add_u32_e32 v234, 0x580000, v233
	global_store_dwordx4 v234, v[240:243], s[6:7]
	s_waitcnt vmcnt(36)
	v_mfma_f32_32x32x16_bf16 v[4:19], v[84:87], v[148:151], 0
	v_mfma_f32_32x32x16_bf16 v[4:19], v[88:91], v[152:155], v[4:19]
	v_xor_b32_e32 v68, 0x80008000, v88
	v_xor_b32_e32 v69, 0x80008000, v89
	v_xor_b32_e32 v70, 0x80008000, v90
	v_xor_b32_e32 v71, 0x80008000, v91
	v_mfma_f32_32x32x16_bf16 v[20:35], v[84:87], v[152:155], 0
	s_nop 0
	v_mfma_f32_32x32x16_bf16 v[20:35], v[68:71], v[148:151], v[20:35]
	v_mfma_f32_32x32x16_bf16 v[4:19], v[92:95], v[156:159], v[4:19]
	v_mfma_f32_32x32x16_bf16 v[4:19], v[96:99], v[160:163], v[4:19]
	v_xor_b32_e32 v68, 0x80008000, v96
	v_xor_b32_e32 v69, 0x80008000, v97
	v_xor_b32_e32 v70, 0x80008000, v98
	v_xor_b32_e32 v71, 0x80008000, v99
	v_mfma_f32_32x32x16_bf16 v[20:35], v[92:95], v[160:163], v[20:35]
	s_nop 0
	v_mfma_f32_32x32x16_bf16 v[20:35], v[68:71], v[156:159], v[20:35]
	v_mfma_f32_32x32x16_bf16 v[4:19], v[100:103], v[164:167], v[4:19]
	v_mfma_f32_32x32x16_bf16 v[4:19], v[104:107], v[168:171], v[4:19]
	v_xor_b32_e32 v68, 0x80008000, v104
	v_xor_b32_e32 v69, 0x80008000, v105
	v_xor_b32_e32 v70, 0x80008000, v106
	v_xor_b32_e32 v71, 0x80008000, v107
	v_mfma_f32_32x32x16_bf16 v[20:35], v[100:103], v[168:171], v[20:35]
	s_nop 0
	v_mfma_f32_32x32x16_bf16 v[20:35], v[68:71], v[164:167], v[20:35]
	v_mfma_f32_32x32x16_bf16 v[4:19], v[108:111], v[172:175], v[4:19]
	v_mfma_f32_32x32x16_bf16 v[4:19], v[112:115], v[176:179], v[4:19]
	v_xor_b32_e32 v68, 0x80008000, v112
	v_xor_b32_e32 v69, 0x80008000, v113
	v_xor_b32_e32 v70, 0x80008000, v114
	v_xor_b32_e32 v71, 0x80008000, v115
	v_mfma_f32_32x32x16_bf16 v[20:35], v[108:111], v[176:179], v[20:35]
	s_nop 0
	v_mfma_f32_32x32x16_bf16 v[20:35], v[68:71], v[172:175], v[20:35]
	v_mfma_f32_32x32x16_bf16 v[4:19], v[116:119], v[180:183], v[4:19]
; __device__ __forceinline__ bf16_t bf1(float v) { return (bf16_t)pk2(v, 0.f); }
; #define LDS_WAIT() asm volatile("s_waitcnt lgkmcnt(0)" ::: "memory")
; __device__ __forceinline__ void dft1_mfma(const bf16_t* U, bf16_t* YB, const bf16_t* A1, const float* TW, LAS unsigned char* tile, int gw, int NGW, int lane) {
;     ...
;                 aR = __builtin_amdgcn_mfma_f32_32x32x16_bf16(ac, br, aR, 0, 0, 0); aR = __builtin_amdgcn_mfma_f32_32x32x16_bf16(as, bi, aR, 0, 0, 0);
;                 aI = __builtin_amdgcn_mfma_f32_32x32x16_bf16(ac, bi, aI, 0, 0, 0); aI = __builtin_amdgcn_mfma_f32_32x32x16_bf16(negbf(as), br, aI, 0, 0, 0);
;             }
; #pragma unroll
;             for (int i = 0; i < 16; ++i) { const int ka = 32 * mb + 8 * (i >> 2) + 4 * hh + (i & 3); const float tc = TW[ka * 64 + sf], ts = TW[8192 + ka * 64 + sf];
;                 const float r2 = tc * aR[i] + ts * aI[i], i2 = tc * aI[i] - ts * aR[i]; bf16_t* op = YB + (size_t)(b * SEQ + ka * 64 + sf) * 512 + 128 * g + 32 * nh + r32;
;                 op[0] = bf1(r2); op[64] = bf1(i2); }
;         }
;         LDS_WAIT();
	v_mfma_f32_32x32x16_bf16 v[4:19], v[120:123], v[184:187], v[4:19]
	v_xor_b32_e32 v68, 0x80008000, v120
	v_xor_b32_e32 v69, 0x80008000, v121
	v_xor_b32_e32 v70, 0x80008000, v122
	v_xor_b32_e32 v71, 0x80008000, v123
	v_mfma_f32_32x32x16_bf16 v[20:35], v[116:119], v[184:187], v[20:35]
	s_nop 0
	v_mfma_f32_32x32x16_bf16 v[20:35], v[68:71], v[180:183], v[20:35]
	v_mfma_f32_32x32x16_bf16 v[4:19], v[124:127], v[188:191], v[4:19]
	v_mfma_f32_32x32x16_bf16 v[4:19], v[128:131], v[192:195], v[4:19]
	v_xor_b32_e32 v68, 0x80008000, v128
	v_xor_b32_e32 v69, 0x80008000, v129
	v_xor_b32_e32 v70, 0x80008000, v130
	v_xor_b32_e32 v71, 0x80008000, v131
	v_mfma_f32_32x32x16_bf16 v[20:35], v[124:127], v[192:195], v[20:35]
	s_nop 0
	v_mfma_f32_32x32x16_bf16 v[20:35], v[68:71], v[188:191], v[20:35]
	v_mfma_f32_32x32x16_bf16 v[4:19], v[132:135], v[196:199], v[4:19]
	v_mfma_f32_32x32x16_bf16 v[4:19], v[136:139], v[200:203], v[4:19]
	v_xor_b32_e32 v68, 0x80008000, v136
	v_xor_b32_e32 v69, 0x80008000, v137
	v_xor_b32_e32 v70, 0x80008000, v138
	v_xor_b32_e32 v71, 0x80008000, v139
	v_mfma_f32_32x32x16_bf16 v[20:35], v[132:135], v[200:203], v[20:35]
	s_nop 0
	v_mfma_f32_32x32x16_bf16 v[20:35], v[68:71], v[196:199], v[20:35]
	v_mfma_f32_32x32x16_bf16 v[4:19], v[140:143], v[204:207], v[4:19]
	v_mfma_f32_32x32x16_bf16 v[4:19], v[60:63], v[64:67], v[4:19]
	v_xor_b32_e32 v68, 0x80008000, v60
	v_xor_b32_e32 v69, 0x80008000, v61
	v_xor_b32_e32 v70, 0x80008000, v62
	v_xor_b32_e32 v71, 0x80008000, v63
	v_mfma_f32_32x32x16_bf16 v[20:35], v[140:143], v[64:67], v[20:35]
	s_nop 0
	v_mfma_f32_32x32x16_bf16 v[20:35], v[68:71], v[204:207], v[20:35]
	s_waitcnt vmcnt(0)
	s_nop 15
	v_mul_f32_e32 v235, v20, v213
	v_mul_f32_e32 v236, v4, v213
	v_fmac_f32_e32 v235, v4, v42
	v_fma_f32 v236, v20, v42, -v236
	v_cvt_pk_bf16_f32 v235, v235, v235
	v_cvt_pk_bf16_f32 v236, v236, v236
	ds_write_b16 v237, v235 offset:12288
	ds_write_b16 v237, v236 offset:12352
	v_mul_f32_e32 v235, v21, v214
	v_mul_f32_e32 v236, v5, v214
	v_fmac_f32_e32 v235, v5, v43
	v_fma_f32 v236, v21, v43, -v236
	v_cvt_pk_bf16_f32 v235, v235, v235
	v_cvt_pk_bf16_f32 v236, v236, v236
	ds_write_b16 v237, v235 offset:12416
	ds_write_b16 v237, v236 offset:12480
	v_mul_f32_e32 v235, v22, v215
	v_mul_f32_e32 v236, v6, v215
	v_fmac_f32_e32 v235, v6, v44
	v_fma_f32 v236, v22, v44, -v236
	v_cvt_pk_bf16_f32 v235, v235, v235
	v_cvt_pk_bf16_f32 v236, v236, v236
	ds_write_b16 v237, v235 offset:12544
	ds_write_b16 v237, v236 offset:12608
	v_mul_f32_e32 v235, v23, v216
	v_mul_f32_e32 v236, v7, v216
	v_fmac_f32_e32 v235, v7, v45
	v_fma_f32 v236, v23, v45, -v236
	v_cvt_pk_bf16_f32 v235, v235, v235
	v_cvt_pk_bf16_f32 v236, v236, v236
	ds_write_b16 v237, v235 offset:12672
	ds_write_b16 v237, v236 offset:12736
	v_mul_f32_e32 v235, v24, v217
	v_mul_f32_e32 v236, v8, v217
	v_fmac_f32_e32 v235, v8, v46
	v_fma_f32 v236, v24, v46, -v236
	v_cvt_pk_bf16_f32 v235, v235, v235
	v_cvt_pk_bf16_f32 v236, v236, v236
	ds_write_b16 v237, v235 offset:13312
	ds_write_b16 v237, v236 offset:13376
	v_mul_f32_e32 v235, v25, v218
	v_mul_f32_e32 v236, v9, v218
	v_fmac_f32_e32 v235, v9, v47
	v_fma_f32 v236, v25, v47, -v236
	v_cvt_pk_bf16_f32 v235, v235, v235
	v_cvt_pk_bf16_f32 v236, v236, v236
	ds_write_b16 v237, v235 offset:13440
	ds_write_b16 v237, v236 offset:13504
	v_mul_f32_e32 v235, v26, v219
	v_mul_f32_e32 v236, v10, v219
	v_fmac_f32_e32 v235, v10, v48
	v_fma_f32 v236, v26, v48, -v236
	v_cvt_pk_bf16_f32 v235, v235, v235
	v_cvt_pk_bf16_f32 v236, v236, v236
	ds_write_b16 v237, v235 offset:13568
	ds_write_b16 v237, v236 offset:13632
	v_mul_f32_e32 v235, v27, v220
	v_mul_f32_e32 v236, v11, v220
	v_fmac_f32_e32 v235, v11, v49
	v_fma_f32 v236, v27, v49, -v236
	v_cvt_pk_bf16_f32 v235, v235, v235
	v_cvt_pk_bf16_f32 v236, v236, v236
	ds_write_b16 v237, v235 offset:13696
	ds_write_b16 v237, v236 offset:13760
	v_mul_f32_e32 v235, v28, v221
	v_mul_f32_e32 v236, v12, v221
	v_fmac_f32_e32 v235, v12, v50
	v_fma_f32 v236, v28, v50, -v236
	v_cvt_pk_bf16_f32 v235, v235, v235
	v_cvt_pk_bf16_f32 v236, v236, v236
	ds_write_b16 v237, v235 offset:14336
	ds_write_b16 v237, v236 offset:14400
	v_mul_f32_e32 v235, v29, v222
	v_mul_f32_e32 v236, v13, v222
	v_fmac_f32_e32 v235, v13, v51
	v_fma_f32 v236, v29, v51, -v236
	v_cvt_pk_bf16_f32 v235, v235, v235
	v_cvt_pk_bf16_f32 v236, v236, v236
	ds_write_b16 v237, v235 offset:14464
	ds_write_b16 v237, v236 offset:14528
	v_mul_f32_e32 v235, v30, v223
	v_mul_f32_e32 v236, v14, v223
	v_fmac_f32_e32 v235, v14, v52
	v_fma_f32 v236, v30, v52, -v236
	v_cvt_pk_bf16_f32 v235, v235, v235
	v_cvt_pk_bf16_f32 v236, v236, v236
	ds_write_b16 v237, v235 offset:14592
	ds_write_b16 v237, v236 offset:14656
	v_mul_f32_e32 v235, v31, v224
	v_mul_f32_e32 v236, v15, v224
	v_fmac_f32_e32 v235, v15, v53
	v_fma_f32 v236, v31, v53, -v236
	v_cvt_pk_bf16_f32 v235, v235, v235
	v_cvt_pk_bf16_f32 v236, v236, v236
	ds_write_b16 v237, v235 offset:14720
	ds_write_b16 v237, v236 offset:14784
	v_mul_f32_e32 v235, v32, v225
	v_mul_f32_e32 v236, v16, v225
	v_fmac_f32_e32 v235, v16, v54
	v_fma_f32 v236, v32, v54, -v236
	v_cvt_pk_bf16_f32 v235, v235, v235
	v_cvt_pk_bf16_f32 v236, v236, v236
	ds_write_b16 v237, v235 offset:15360
	ds_write_b16 v237, v236 offset:15424
	v_mul_f32_e32 v235, v33, v226
	v_mul_f32_e32 v236, v17, v226
	v_fmac_f32_e32 v235, v17, v55
	v_fma_f32 v236, v33, v55, -v236
	v_cvt_pk_bf16_f32 v235, v235, v235
	v_cvt_pk_bf16_f32 v236, v236, v236
	ds_write_b16 v237, v235 offset:15488
	ds_write_b16 v237, v236 offset:15552
	v_mul_f32_e32 v235, v34, v227
	v_mul_f32_e32 v236, v18, v227
	v_fmac_f32_e32 v235, v18, v56
	v_fma_f32 v236, v34, v56, -v236
	v_cvt_pk_bf16_f32 v235, v235, v235
	v_cvt_pk_bf16_f32 v236, v236, v236
	ds_write_b16 v237, v235 offset:15616
	ds_write_b16 v237, v236 offset:15680
	v_mul_f32_e32 v235, v35, v228
	v_mul_f32_e32 v236, v19, v228
	v_fmac_f32_e32 v235, v19, v57
	v_fma_f32 v236, v35, v57, -v236
	v_cvt_pk_bf16_f32 v235, v235, v235
	v_cvt_pk_bf16_f32 v236, v236, v236
	ds_write_b16 v237, v235 offset:15744
	ds_write_b16 v237, v236 offset:15808
	s_waitcnt lgkmcnt(0)
	ds_read_b128 v[76:79], v239 offset:12288
	ds_read_b128 v[244:247], v239 offset:13312
	ds_read_b128 v[250:253], v239 offset:14336
	ds_read_b128 v[240:243], v239 offset:15360
	s_waitcnt lgkmcnt(3)
	v_add_u32_e32 v234, 0x600000, v233
	global_store_dwordx4 v234, v[76:79], s[6:7]
	s_waitcnt lgkmcnt(2)
	v_add_u32_e32 v234, 0x680000, v233
	global_store_dwordx4 v234, v[244:247], s[6:7]
	s_waitcnt lgkmcnt(1)
	v_add_u32_e32 v234, 0x700000, v233
	global_store_dwordx4 v234, v[250:253], s[6:7]
	s_waitcnt lgkmcnt(0)
	v_add_u32_e32 v234, 0x780000, v233
	global_store_dwordx4 v234, v[240:243], s[6:7]
	s_waitcnt lgkmcnt(0)
	s_cbranch_scc0 .LBB0_697
	s_branch .LBB0_181
